# write-through (sc1) for the elementwise phase's 16-byte streaming stores (next-layer weights, conv rows) ahead of the device-scope barrier
# speedup vs baseline: 1.0027x; 1.0027x over previous
; __device__ __forceinline__ float bf_lo(unsigned w) { return __uint_as_float(w << 16); }
; __global__ void __launch_bounds__(512, 2) trunk_fwd(Args args) {
;     ...
;             for (int ch = gw; ch < M / 16; ch += NGW) {
;                 const int r0 = ch * 16, t0 = r0 & (SEQ - 1), c0 = lane * 8;
;                 float w0[8], w1[8], w2[8], u1[8], u2[8];
; #pragma unroll
;                 for (int i = 0; i < 8; ++i) { w0[i] = cw[c0 + i]; w1[i] = cw[512 + c0 + i]; w2[i] = cw[1024 + c0 + i]; u1[i] = 0.f; u2[i] = 0.f; }
;                 if (t0 != 0) {
;                     const u32x4 c1 = *(const u32x4*)(Z + (size_t)(r0 - 1) * INP + 1280 + c0), c2 = *(const u32x4*)(Z + (size_t)(r0 - 2) * INP + 1280 + c0);
; #pragma unroll
;                     for (int i = 0; i < 4; ++i) { u1[2 * i] = bf_lo(c1[i]); u1[2 * i + 1] = bf_hi(c1[i]); u2[2 * i] = bf_lo(c2[i]); u2[2 * i + 1] = bf_hi(c2[i]); }
;                 }
;                 u32x4 gb_n = *(const u32x4*)(Z + (size_t)r0 * INP + 768 + c0), gu_n = *(const u32x4*)(Z + (size_t)r0 * INP + 1280 + c0);
;                 f32x4 pv_n = *(const f32x4*)(pl + (size_t)r0 * PLE + lane * 4);
; #pragma nounroll
;                 for (int rr = 0; rr < 16; ++rr) {
;                     const int r = r0 + rr;
;                     const u32x4 gb = gb_n, gu = gu_n; const f32x4 pv4 = pv_n;
;                     if (rr < 15) { gb_n = *(const u32x4*)(Z + (size_t)(r + 1) * INP + 768 + c0); gu_n = *(const u32x4*)(Z + (size_t)(r + 1) * INP + 1280 + c0);
;                                    pv_n = *(const f32x4*)(pl + (size_t)(r + 1) * PLE + lane * 4); }
;                     float cv[8], uu[8]; float ss = 0.f;
; #pragma unroll
;                     for (int i = 0; i < 4; ++i) {
;                         uu[2 * i] = bf_lo(gu[i]); uu[2 * i + 1] = bf_hi(gu[i]);
;                         cv[2 * i] = bf_lo(gb[i]) * (w0[2 * i] * uu[2 * i] + w1[2 * i] * u1[2 * i] + w2[2 * i] * u2[2 * i]);
;                         cv[2 * i + 1] = bf_hi(gb[i]) * (w0[2 * i + 1] * uu[2 * i + 1] + w1[2 * i + 1] * u1[2 * i + 1] + w2[2 * i + 1] * u2[2 * i + 1]);
;                     }
; #pragma unroll
;                     for (int i = 0; i < 8; ++i) { ss += cv[i] * cv[i]; u2[i] = u1[i]; u1[i] = uu[i]; }
;                     ss = wave_sum(ss);
;                     const float rc = rsqrtf(ss * (1.0f / 512.0f) + EPS);
;                     u32x4 oc;
; #pragma unroll
.Lcv_taps_ok:
	v_mad_i64_i32 v[152:153], vcc, s41, v221, v[58:59]
	s_add_u32 s41, s41, 1
	global_load_dwordx4 v[2:5], v[152:153], off offset:1536
	global_load_dwordx4 v[18:21], v[152:153], off offset:2560
	v_mad_i64_i32 v[152:153], vcc, s41, v221, v[58:59]
	s_add_u32 s41, s41, 1
	global_load_dwordx4 v[6:9], v[152:153], off offset:1536
	global_load_dwordx4 v[22:25], v[152:153], off offset:2560
	v_mad_i64_i32 v[152:153], vcc, s41, v221, v[58:59]
	s_add_u32 s41, s41, 1
	global_load_dwordx4 v[10:13], v[152:153], off offset:1536
	global_load_dwordx4 v[26:29], v[152:153], off offset:2560
	v_mad_i64_i32 v[152:153], vcc, s41, v221, v[58:59]
	s_add_u32 s41, s41, 1
	global_load_dwordx4 v[14:17], v[152:153], off offset:1536
	global_load_dwordx4 v[30:33], v[152:153], off offset:2560
	s_waitcnt vmcnt(6)
	v_lshlrev_b32_e32 v188, 16, v18
	v_and_b32_e32 v189, 0xffff0000, v18
	v_lshlrev_b32_e32 v190, 16, v19
	v_and_b32_e32 v191, 0xffff0000, v19
	v_lshlrev_b32_e32 v192, 16, v20
	v_and_b32_e32 v193, 0xffff0000, v20
	v_lshlrev_b32_e32 v194, 16, v21
	v_and_b32_e32 v195, 0xffff0000, v21
	v_mul_f32_e32 v140, v164, v188
	v_mul_f32_e32 v141, v165, v189
	v_mul_f32_e32 v142, v166, v190
	v_mul_f32_e32 v143, v167, v191
	v_mul_f32_e32 v144, v168, v192
	v_mul_f32_e32 v145, v169, v193
	v_mul_f32_e32 v146, v170, v194
	v_mul_f32_e32 v147, v171, v195
	v_fmac_f32_e32 v140, v172, v204
	v_fmac_f32_e32 v141, v173, v205
	v_fmac_f32_e32 v142, v174, v206
	v_fmac_f32_e32 v143, v175, v207
	v_fmac_f32_e32 v144, v176, v208
	v_fmac_f32_e32 v145, v177, v209
	v_fmac_f32_e32 v146, v178, v210
	v_fmac_f32_e32 v147, v179, v211
	v_fmac_f32_e32 v140, v180, v196
	v_fmac_f32_e32 v141, v181, v197
	v_fmac_f32_e32 v142, v182, v198
	v_fmac_f32_e32 v143, v183, v199
	v_fmac_f32_e32 v144, v184, v200
	v_fmac_f32_e32 v145, v185, v201
	v_fmac_f32_e32 v146, v186, v202
	v_fmac_f32_e32 v147, v187, v203
	v_lshlrev_b32_e32 v150, 16, v2
	v_and_b32_e32 v151, 0xffff0000, v2
	v_mul_f32_e32 v140, v150, v140
	v_mul_f32_e32 v141, v151, v141
	v_lshlrev_b32_e32 v150, 16, v3
	v_and_b32_e32 v151, 0xffff0000, v3
	v_mul_f32_e32 v142, v150, v142
	v_mul_f32_e32 v143, v151, v143
	v_lshlrev_b32_e32 v150, 16, v4
	v_and_b32_e32 v151, 0xffff0000, v4
	v_mul_f32_e32 v144, v150, v144
	v_mul_f32_e32 v145, v151, v145
	v_lshlrev_b32_e32 v150, 16, v5
	v_and_b32_e32 v151, 0xffff0000, v5
	v_mul_f32_e32 v146, v150, v146
	v_mul_f32_e32 v147, v151, v147
	v_mul_f32_e32 v148, v140, v140
	v_fmac_f32_e32 v148, v141, v141
	v_fmac_f32_e32 v148, v142, v142
	v_fmac_f32_e32 v148, v143, v143
	v_fmac_f32_e32 v148, v144, v144
	v_fmac_f32_e32 v148, v145, v145
	v_fmac_f32_e32 v148, v146, v146
	v_fmac_f32_e32 v148, v147, v147
	v_mad_i64_i32 v[152:153], vcc, s41, v221, v[58:59]
	s_add_u32 s41, s41, 1
	global_load_dwordx4 v[2:5], v[152:153], off offset:1536
	global_load_dwordx4 v[18:21], v[152:153], off offset:2560
	s_nop 1
	v_add_f32_dpp v148, v148, v148 quad_perm:[1,0,3,2] row_mask:0xf bank_mask:0xf
	s_nop 1
	v_add_f32_dpp v148, v148, v148 quad_perm:[2,3,0,1] row_mask:0xf bank_mask:0xf
	s_nop 1
	v_add_f32_dpp v148, v148, v148 row_half_mirror row_mask:0xf bank_mask:0xf
	s_nop 1
	v_add_f32_dpp v148, v148, v148 row_mirror row_mask:0xf bank_mask:0xf
	s_nop 1
	v_add_f32_dpp v148, v148, v148 row_bcast:15 row_mask:0xa bank_mask:0xf
	s_nop 1
	v_add_f32_dpp v148, v148, v148 row_bcast:31 row_mask:0xc bank_mask:0xf
	s_nop 0
	v_readlane_b32 s0, v148, 63
	s_nop 1
	v_mov_b32_e32 v148, s0
	v_fmamk_f32 v148, v148, 0x3b000000, v162
	v_mul_f32_e32 v150, 0x4b800000, v148
	v_cmp_gt_f32_e32 vcc, s31, v148
	s_nop 1
	v_cndmask_b32_e32 v148, v148, v150, vcc
	v_rsq_f32_e32 v148, v148
	s_nop 0
	v_mul_f32_e32 v150, 0x45800000, v148
	v_cndmask_b32_e32 v149, v148, v150, vcc
	v_mul_f32_e32 v140, v149, v140
	v_mul_f32_e32 v141, v149, v141
	v_mul_f32_e32 v142, v149, v142
	v_mul_f32_e32 v143, v149, v143
	v_mul_f32_e32 v144, v149, v144
	v_mul_f32_e32 v145, v149, v145
	v_mul_f32_e32 v146, v149, v146
	v_mul_f32_e32 v147, v149, v147
	v_cvt_pk_bf16_f32 v140, v140, v141
	v_cvt_pk_bf16_f32 v141, v142, v143
	v_cvt_pk_bf16_f32 v142, v144, v145
	v_cvt_pk_bf16_f32 v143, v146, v147
	global_store_dwordx4 v[156:157], v[140:143], off sc1
	s_waitcnt vmcnt(7)
	v_lshlrev_b32_e32 v196, 16, v22
	v_and_b32_e32 v197, 0xffff0000, v22
	v_lshlrev_b32_e32 v198, 16, v23
	v_and_b32_e32 v199, 0xffff0000, v23
	v_lshlrev_b32_e32 v200, 16, v24
	v_and_b32_e32 v201, 0xffff0000, v24
	v_lshlrev_b32_e32 v202, 16, v25
	v_and_b32_e32 v203, 0xffff0000, v25
	v_mul_f32_e32 v140, v164, v196
	v_mul_f32_e32 v141, v165, v197
	v_mul_f32_e32 v142, v166, v198
	v_mul_f32_e32 v143, v167, v199
	v_mul_f32_e32 v144, v168, v200
	v_mul_f32_e32 v145, v169, v201
	v_mul_f32_e32 v146, v170, v202
	v_mul_f32_e32 v147, v171, v203
	v_fmac_f32_e32 v140, v172, v188
	v_fmac_f32_e32 v141, v173, v189
	v_fmac_f32_e32 v142, v174, v190
	v_fmac_f32_e32 v143, v175, v191
	v_fmac_f32_e32 v144, v176, v192
	v_fmac_f32_e32 v145, v177, v193
	v_fmac_f32_e32 v146, v178, v194
	v_fmac_f32_e32 v147, v179, v195
	v_fmac_f32_e32 v140, v180, v204
	v_fmac_f32_e32 v141, v181, v205
	v_fmac_f32_e32 v142, v182, v206
	v_fmac_f32_e32 v143, v183, v207
	v_fmac_f32_e32 v144, v184, v208
	v_fmac_f32_e32 v145, v185, v209
	v_fmac_f32_e32 v146, v186, v210
	v_fmac_f32_e32 v147, v187, v211
	v_lshlrev_b32_e32 v150, 16, v6
	v_and_b32_e32 v151, 0xffff0000, v6
	v_mul_f32_e32 v140, v150, v140
	v_mul_f32_e32 v141, v151, v141
	v_lshlrev_b32_e32 v150, 16, v7
	v_and_b32_e32 v151, 0xffff0000, v7
	v_mul_f32_e32 v142, v150, v142
	v_mul_f32_e32 v143, v151, v143
	v_lshlrev_b32_e32 v150, 16, v8
	v_and_b32_e32 v151, 0xffff0000, v8
	v_mul_f32_e32 v144, v150, v144
	v_mul_f32_e32 v145, v151, v145
; __device__ __forceinline__ float bf_lo(unsigned w) { return __uint_as_float(w << 16); }
; __global__ void __launch_bounds__(512, 2) trunk_fwd(Args args) {
;     ...
;             for (int ch = gw; ch < M / 16; ch += NGW) {
;                 const int r0 = ch * 16, t0 = r0 & (SEQ - 1), c0 = lane * 8;
;                 float w0[8], w1[8], w2[8], u1[8], u2[8];
; #pragma unroll
;                 for (int i = 0; i < 8; ++i) { w0[i] = cw[c0 + i]; w1[i] = cw[512 + c0 + i]; w2[i] = cw[1024 + c0 + i]; u1[i] = 0.f; u2[i] = 0.f; }
;                 if (t0 != 0) {
;                     const u32x4 c1 = *(const u32x4*)(Z + (size_t)(r0 - 1) * INP + 1280 + c0), c2 = *(const u32x4*)(Z + (size_t)(r0 - 2) * INP + 1280 + c0);
; #pragma unroll
;                     for (int i = 0; i < 4; ++i) { u1[2 * i] = bf_lo(c1[i]); u1[2 * i + 1] = bf_hi(c1[i]); u2[2 * i] = bf_lo(c2[i]); u2[2 * i + 1] = bf_hi(c2[i]); }
;                 }
;                 u32x4 gb_n = *(const u32x4*)(Z + (size_t)r0 * INP + 768 + c0), gu_n = *(const u32x4*)(Z + (size_t)r0 * INP + 1280 + c0);
;                 f32x4 pv_n = *(const f32x4*)(pl + (size_t)r0 * PLE + lane * 4);
; #pragma nounroll
;                 for (int rr = 0; rr < 16; ++rr) {
;                     const int r = r0 + rr;
;                     const u32x4 gb = gb_n, gu = gu_n; const f32x4 pv4 = pv_n;
;                     if (rr < 15) { gb_n = *(const u32x4*)(Z + (size_t)(r + 1) * INP + 768 + c0); gu_n = *(const u32x4*)(Z + (size_t)(r + 1) * INP + 1280 + c0);
;                                    pv_n = *(const f32x4*)(pl + (size_t)(r + 1) * PLE + lane * 4); }
;                     float cv[8], uu[8]; float ss = 0.f;
; #pragma unroll
;                     for (int i = 0; i < 4; ++i) {
;                         uu[2 * i] = bf_lo(gu[i]); uu[2 * i + 1] = bf_hi(gu[i]);
;                         cv[2 * i] = bf_lo(gb[i]) * (w0[2 * i] * uu[2 * i] + w1[2 * i] * u1[2 * i] + w2[2 * i] * u2[2 * i]);
;                         cv[2 * i + 1] = bf_hi(gb[i]) * (w0[2 * i + 1] * uu[2 * i + 1] + w1[2 * i + 1] * u1[2 * i + 1] + w2[2 * i + 1] * u2[2 * i + 1]);
;                     }
; #pragma unroll
;                     for (int i = 0; i < 8; ++i) { ss += cv[i] * cv[i]; u2[i] = u1[i]; u1[i] = uu[i]; }
;                     ss = wave_sum(ss);
;                     const float rc = rsqrtf(ss * (1.0f / 512.0f) + EPS);
;                     u32x4 oc;
; #pragma unroll
	v_lshlrev_b32_e32 v150, 16, v9
	v_and_b32_e32 v151, 0xffff0000, v9
	v_mul_f32_e32 v146, v150, v146
	v_mul_f32_e32 v147, v151, v147
	v_mul_f32_e32 v148, v140, v140
	v_fmac_f32_e32 v148, v141, v141
	v_fmac_f32_e32 v148, v142, v142
	v_fmac_f32_e32 v148, v143, v143
	v_fmac_f32_e32 v148, v144, v144
	v_fmac_f32_e32 v148, v145, v145
	v_fmac_f32_e32 v148, v146, v146
	v_fmac_f32_e32 v148, v147, v147
	v_mad_i64_i32 v[152:153], vcc, s41, v221, v[58:59]
	s_add_u32 s41, s41, 1
	global_load_dwordx4 v[6:9], v[152:153], off offset:1536
	global_load_dwordx4 v[22:25], v[152:153], off offset:2560
	s_nop 1
	v_add_f32_dpp v148, v148, v148 quad_perm:[1,0,3,2] row_mask:0xf bank_mask:0xf
	s_nop 1
	v_add_f32_dpp v148, v148, v148 quad_perm:[2,3,0,1] row_mask:0xf bank_mask:0xf
	s_nop 1
	v_add_f32_dpp v148, v148, v148 row_half_mirror row_mask:0xf bank_mask:0xf
	s_nop 1
	v_add_f32_dpp v148, v148, v148 row_mirror row_mask:0xf bank_mask:0xf
	s_nop 1
	v_add_f32_dpp v148, v148, v148 row_bcast:15 row_mask:0xa bank_mask:0xf
	s_nop 1
	v_add_f32_dpp v148, v148, v148 row_bcast:31 row_mask:0xc bank_mask:0xf
	s_nop 0
	v_readlane_b32 s0, v148, 63
	s_nop 1
	v_mov_b32_e32 v148, s0
	v_fmamk_f32 v148, v148, 0x3b000000, v162
	v_mul_f32_e32 v150, 0x4b800000, v148
	v_cmp_gt_f32_e32 vcc, s31, v148
	s_nop 1
	v_cndmask_b32_e32 v148, v148, v150, vcc
	v_rsq_f32_e32 v148, v148
	s_nop 0
	v_mul_f32_e32 v150, 0x45800000, v148
	v_cndmask_b32_e32 v149, v148, v150, vcc
	v_mul_f32_e32 v140, v149, v140
	v_mul_f32_e32 v141, v149, v141
	v_mul_f32_e32 v142, v149, v142
	v_mul_f32_e32 v143, v149, v143
	v_mul_f32_e32 v144, v149, v144
	v_mul_f32_e32 v145, v149, v145
	v_mul_f32_e32 v146, v149, v146
	v_mul_f32_e32 v147, v149, v147
	v_cvt_pk_bf16_f32 v140, v140, v141
	v_cvt_pk_bf16_f32 v141, v142, v143
	v_cvt_pk_bf16_f32 v142, v144, v145
	v_cvt_pk_bf16_f32 v143, v146, v147
	global_store_dwordx4 v[156:157], v[140:143], off offset:2048 sc1
	v_lshl_add_u64 v[156:157], v[156:157], 0, s[20:21]
	s_waitcnt vmcnt(8)
	v_lshlrev_b32_e32 v204, 16, v26
	v_and_b32_e32 v205, 0xffff0000, v26
	v_lshlrev_b32_e32 v206, 16, v27
	v_and_b32_e32 v207, 0xffff0000, v27
	v_lshlrev_b32_e32 v208, 16, v28
	v_and_b32_e32 v209, 0xffff0000, v28
	v_lshlrev_b32_e32 v210, 16, v29
	v_and_b32_e32 v211, 0xffff0000, v29
	v_mul_f32_e32 v140, v164, v204
	v_mul_f32_e32 v141, v165, v205
	v_mul_f32_e32 v142, v166, v206
	v_mul_f32_e32 v143, v167, v207
	v_mul_f32_e32 v144, v168, v208
	v_mul_f32_e32 v145, v169, v209
	v_mul_f32_e32 v146, v170, v210
	v_mul_f32_e32 v147, v171, v211
	v_fmac_f32_e32 v140, v172, v196
	v_fmac_f32_e32 v141, v173, v197
	v_fmac_f32_e32 v142, v174, v198
	v_fmac_f32_e32 v143, v175, v199
	v_fmac_f32_e32 v144, v176, v200
	v_fmac_f32_e32 v145, v177, v201
	v_fmac_f32_e32 v146, v178, v202
	v_fmac_f32_e32 v147, v179, v203
	v_fmac_f32_e32 v140, v180, v188
	v_fmac_f32_e32 v141, v181, v189
	v_fmac_f32_e32 v142, v182, v190
	v_fmac_f32_e32 v143, v183, v191
	v_fmac_f32_e32 v144, v184, v192
	v_fmac_f32_e32 v145, v185, v193
	v_fmac_f32_e32 v146, v186, v194
	v_fmac_f32_e32 v147, v187, v195
	v_lshlrev_b32_e32 v150, 16, v10
	v_and_b32_e32 v151, 0xffff0000, v10
	v_mul_f32_e32 v140, v150, v140
	v_mul_f32_e32 v141, v151, v141
	v_lshlrev_b32_e32 v150, 16, v11
	v_and_b32_e32 v151, 0xffff0000, v11
	v_mul_f32_e32 v142, v150, v142
	v_mul_f32_e32 v143, v151, v143
	v_lshlrev_b32_e32 v150, 16, v12
	v_and_b32_e32 v151, 0xffff0000, v12
	v_mul_f32_e32 v144, v150, v144
	v_mul_f32_e32 v145, v151, v145
	v_lshlrev_b32_e32 v150, 16, v13
	v_and_b32_e32 v151, 0xffff0000, v13
	v_mul_f32_e32 v146, v150, v146
	v_mul_f32_e32 v147, v151, v147
	v_mul_f32_e32 v148, v140, v140
	v_fmac_f32_e32 v148, v141, v141
	v_fmac_f32_e32 v148, v142, v142
	v_fmac_f32_e32 v148, v143, v143
	v_fmac_f32_e32 v148, v144, v144
	v_fmac_f32_e32 v148, v145, v145
	v_fmac_f32_e32 v148, v146, v146
	v_fmac_f32_e32 v148, v147, v147
	v_mad_i64_i32 v[152:153], vcc, s41, v221, v[58:59]
	s_add_u32 s41, s41, 1
	global_load_dwordx4 v[10:13], v[152:153], off offset:1536
	global_load_dwordx4 v[26:29], v[152:153], off offset:2560
	s_nop 1
	v_add_f32_dpp v148, v148, v148 quad_perm:[1,0,3,2] row_mask:0xf bank_mask:0xf
	s_nop 1
	v_add_f32_dpp v148, v148, v148 quad_perm:[2,3,0,1] row_mask:0xf bank_mask:0xf
	s_nop 1
	v_add_f32_dpp v148, v148, v148 row_half_mirror row_mask:0xf bank_mask:0xf
	s_nop 1
	v_add_f32_dpp v148, v148, v148 row_mirror row_mask:0xf bank_mask:0xf
	s_nop 1
	v_add_f32_dpp v148, v148, v148 row_bcast:15 row_mask:0xa bank_mask:0xf
	s_nop 1
	v_add_f32_dpp v148, v148, v148 row_bcast:31 row_mask:0xc bank_mask:0xf
	s_nop 0
	v_readlane_b32 s0, v148, 63
	s_nop 1
	v_mov_b32_e32 v148, s0
	v_fmamk_f32 v148, v148, 0x3b000000, v162
	v_mul_f32_e32 v150, 0x4b800000, v148
	v_cmp_gt_f32_e32 vcc, s31, v148
	s_nop 1
	v_cndmask_b32_e32 v148, v148, v150, vcc
	v_rsq_f32_e32 v148, v148
	s_nop 0
	v_mul_f32_e32 v150, 0x45800000, v148
	v_cndmask_b32_e32 v149, v148, v150, vcc
	v_mul_f32_e32 v140, v149, v140
	v_mul_f32_e32 v141, v149, v141
	v_mul_f32_e32 v142, v149, v142
	v_mul_f32_e32 v143, v149, v143
	v_mul_f32_e32 v144, v149, v144
	v_mul_f32_e32 v145, v149, v145
	v_mul_f32_e32 v146, v149, v146
	v_mul_f32_e32 v147, v149, v147
	v_cvt_pk_bf16_f32 v140, v140, v141
	v_cvt_pk_bf16_f32 v141, v142, v143
	v_cvt_pk_bf16_f32 v142, v144, v145
	v_cvt_pk_bf16_f32 v143, v146, v147
	global_store_dwordx4 v[156:157], v[140:143], off sc1
	s_waitcnt vmcnt(9)
; __device__ __forceinline__ float bf_lo(unsigned w) { return __uint_as_float(w << 16); }
; __global__ void __launch_bounds__(512, 2) trunk_fwd(Args args) {
;     ...
;             for (int ch = gw; ch < M / 16; ch += NGW) {
;                 const int r0 = ch * 16, t0 = r0 & (SEQ - 1), c0 = lane * 8;
;                 float w0[8], w1[8], w2[8], u1[8], u2[8];
; #pragma unroll
;                 for (int i = 0; i < 8; ++i) { w0[i] = cw[c0 + i]; w1[i] = cw[512 + c0 + i]; w2[i] = cw[1024 + c0 + i]; u1[i] = 0.f; u2[i] = 0.f; }
;                 if (t0 != 0) {
;                     const u32x4 c1 = *(const u32x4*)(Z + (size_t)(r0 - 1) * INP + 1280 + c0), c2 = *(const u32x4*)(Z + (size_t)(r0 - 2) * INP + 1280 + c0);
; #pragma unroll
;                     for (int i = 0; i < 4; ++i) { u1[2 * i] = bf_lo(c1[i]); u1[2 * i + 1] = bf_hi(c1[i]); u2[2 * i] = bf_lo(c2[i]); u2[2 * i + 1] = bf_hi(c2[i]); }
;                 }
;                 u32x4 gb_n = *(const u32x4*)(Z + (size_t)r0 * INP + 768 + c0), gu_n = *(const u32x4*)(Z + (size_t)r0 * INP + 1280 + c0);
;                 f32x4 pv_n = *(const f32x4*)(pl + (size_t)r0 * PLE + lane * 4);
; #pragma nounroll
;                 for (int rr = 0; rr < 16; ++rr) {
;                     const int r = r0 + rr;
;                     const u32x4 gb = gb_n, gu = gu_n; const f32x4 pv4 = pv_n;
;                     if (rr < 15) { gb_n = *(const u32x4*)(Z + (size_t)(r + 1) * INP + 768 + c0); gu_n = *(const u32x4*)(Z + (size_t)(r + 1) * INP + 1280 + c0);
;                                    pv_n = *(const f32x4*)(pl + (size_t)(r + 1) * PLE + lane * 4); }
;                     float cv[8], uu[8]; float ss = 0.f;
; #pragma unroll
;                     for (int i = 0; i < 4; ++i) {
;                         uu[2 * i] = bf_lo(gu[i]); uu[2 * i + 1] = bf_hi(gu[i]);
;                         cv[2 * i] = bf_lo(gb[i]) * (w0[2 * i] * uu[2 * i] + w1[2 * i] * u1[2 * i] + w2[2 * i] * u2[2 * i]);
;                         cv[2 * i + 1] = bf_hi(gb[i]) * (w0[2 * i + 1] * uu[2 * i + 1] + w1[2 * i + 1] * u1[2 * i + 1] + w2[2 * i + 1] * u2[2 * i + 1]);
;                     }
; #pragma unroll
;                     for (int i = 0; i < 8; ++i) { ss += cv[i] * cv[i]; u2[i] = u1[i]; u1[i] = uu[i]; }
;                     ss = wave_sum(ss);
;                     const float rc = rsqrtf(ss * (1.0f / 512.0f) + EPS);
;                     u32x4 oc;
; #pragma unroll
	v_lshlrev_b32_e32 v188, 16, v30
	v_and_b32_e32 v189, 0xffff0000, v30
	v_lshlrev_b32_e32 v190, 16, v31
	v_and_b32_e32 v191, 0xffff0000, v31
	v_lshlrev_b32_e32 v192, 16, v32
	v_and_b32_e32 v193, 0xffff0000, v32
	v_lshlrev_b32_e32 v194, 16, v33
	v_and_b32_e32 v195, 0xffff0000, v33
	v_mul_f32_e32 v140, v164, v188
	v_mul_f32_e32 v141, v165, v189
	v_mul_f32_e32 v142, v166, v190
	v_mul_f32_e32 v143, v167, v191
	v_mul_f32_e32 v144, v168, v192
	v_mul_f32_e32 v145, v169, v193
	v_mul_f32_e32 v146, v170, v194
	v_mul_f32_e32 v147, v171, v195
	v_fmac_f32_e32 v140, v172, v204
	v_fmac_f32_e32 v141, v173, v205
	v_fmac_f32_e32 v142, v174, v206
	v_fmac_f32_e32 v143, v175, v207
	v_fmac_f32_e32 v144, v176, v208
	v_fmac_f32_e32 v145, v177, v209
	v_fmac_f32_e32 v146, v178, v210
	v_fmac_f32_e32 v147, v179, v211
	v_fmac_f32_e32 v140, v180, v196
	v_fmac_f32_e32 v141, v181, v197
	v_fmac_f32_e32 v142, v182, v198
	v_fmac_f32_e32 v143, v183, v199
	v_fmac_f32_e32 v144, v184, v200
	v_fmac_f32_e32 v145, v185, v201
	v_fmac_f32_e32 v146, v186, v202
	v_fmac_f32_e32 v147, v187, v203
	v_lshlrev_b32_e32 v150, 16, v14
	v_and_b32_e32 v151, 0xffff0000, v14
	v_mul_f32_e32 v140, v150, v140
	v_mul_f32_e32 v141, v151, v141
	v_lshlrev_b32_e32 v150, 16, v15
	v_and_b32_e32 v151, 0xffff0000, v15
	v_mul_f32_e32 v142, v150, v142
	v_mul_f32_e32 v143, v151, v143
	v_lshlrev_b32_e32 v150, 16, v16
	v_and_b32_e32 v151, 0xffff0000, v16
	v_mul_f32_e32 v144, v150, v144
	v_mul_f32_e32 v145, v151, v145
	v_lshlrev_b32_e32 v150, 16, v17
	v_and_b32_e32 v151, 0xffff0000, v17
	v_mul_f32_e32 v146, v150, v146
	v_mul_f32_e32 v147, v151, v147
	v_mul_f32_e32 v148, v140, v140
	v_fmac_f32_e32 v148, v141, v141
	v_fmac_f32_e32 v148, v142, v142
	v_fmac_f32_e32 v148, v143, v143
	v_fmac_f32_e32 v148, v144, v144
	v_fmac_f32_e32 v148, v145, v145
	v_fmac_f32_e32 v148, v146, v146
	v_fmac_f32_e32 v148, v147, v147
	v_mad_i64_i32 v[152:153], vcc, s41, v221, v[58:59]
	s_add_u32 s41, s41, 1
	global_load_dwordx4 v[14:17], v[152:153], off offset:1536
	global_load_dwordx4 v[30:33], v[152:153], off offset:2560
	s_nop 1
	v_add_f32_dpp v148, v148, v148 quad_perm:[1,0,3,2] row_mask:0xf bank_mask:0xf
	s_nop 1
	v_add_f32_dpp v148, v148, v148 quad_perm:[2,3,0,1] row_mask:0xf bank_mask:0xf
	s_nop 1
	v_add_f32_dpp v148, v148, v148 row_half_mirror row_mask:0xf bank_mask:0xf
	s_nop 1
	v_add_f32_dpp v148, v148, v148 row_mirror row_mask:0xf bank_mask:0xf
	s_nop 1
	v_add_f32_dpp v148, v148, v148 row_bcast:15 row_mask:0xa bank_mask:0xf
	s_nop 1
	v_add_f32_dpp v148, v148, v148 row_bcast:31 row_mask:0xc bank_mask:0xf
	s_nop 0
	v_readlane_b32 s0, v148, 63
	s_nop 1
	v_mov_b32_e32 v148, s0
	v_fmamk_f32 v148, v148, 0x3b000000, v162
	v_mul_f32_e32 v150, 0x4b800000, v148
	v_cmp_gt_f32_e32 vcc, s31, v148
	s_nop 1
	v_cndmask_b32_e32 v148, v148, v150, vcc
	v_rsq_f32_e32 v148, v148
	s_nop 0
	v_mul_f32_e32 v150, 0x45800000, v148
	v_cndmask_b32_e32 v149, v148, v150, vcc
	v_mul_f32_e32 v140, v149, v140
	v_mul_f32_e32 v141, v149, v141
	v_mul_f32_e32 v142, v149, v142
	v_mul_f32_e32 v143, v149, v143
	v_mul_f32_e32 v144, v149, v144
	v_mul_f32_e32 v145, v149, v145
	v_mul_f32_e32 v146, v149, v146
	v_mul_f32_e32 v147, v149, v147
	v_cvt_pk_bf16_f32 v140, v140, v141
	v_cvt_pk_bf16_f32 v141, v142, v143
	v_cvt_pk_bf16_f32 v142, v144, v145
	v_cvt_pk_bf16_f32 v143, v146, v147
	global_store_dwordx4 v[156:157], v[140:143], off offset:2048 sc1
	v_lshl_add_u64 v[156:157], v[156:157], 0, s[20:21]
	s_waitcnt vmcnt(10)
	v_lshlrev_b32_e32 v196, 16, v18
	v_and_b32_e32 v197, 0xffff0000, v18
	v_lshlrev_b32_e32 v198, 16, v19
	v_and_b32_e32 v199, 0xffff0000, v19
	v_lshlrev_b32_e32 v200, 16, v20
	v_and_b32_e32 v201, 0xffff0000, v20
	v_lshlrev_b32_e32 v202, 16, v21
	v_and_b32_e32 v203, 0xffff0000, v21
	v_mul_f32_e32 v140, v164, v196
	v_mul_f32_e32 v141, v165, v197
	v_mul_f32_e32 v142, v166, v198
	v_mul_f32_e32 v143, v167, v199
	v_mul_f32_e32 v144, v168, v200
	v_mul_f32_e32 v145, v169, v201
	v_mul_f32_e32 v146, v170, v202
	v_mul_f32_e32 v147, v171, v203
	v_fmac_f32_e32 v140, v172, v188
	v_fmac_f32_e32 v141, v173, v189
	v_fmac_f32_e32 v142, v174, v190
	v_fmac_f32_e32 v143, v175, v191
	v_fmac_f32_e32 v144, v176, v192
	v_fmac_f32_e32 v145, v177, v193
	v_fmac_f32_e32 v146, v178, v194
	v_fmac_f32_e32 v147, v179, v195
	v_fmac_f32_e32 v140, v180, v204
	v_fmac_f32_e32 v141, v181, v205
	v_fmac_f32_e32 v142, v182, v206
	v_fmac_f32_e32 v143, v183, v207
	v_fmac_f32_e32 v144, v184, v208
	v_fmac_f32_e32 v145, v185, v209
	v_fmac_f32_e32 v146, v186, v210
	v_fmac_f32_e32 v147, v187, v211
	v_lshlrev_b32_e32 v150, 16, v2
	v_and_b32_e32 v151, 0xffff0000, v2
	v_mul_f32_e32 v140, v150, v140
	v_mul_f32_e32 v141, v151, v141
	v_lshlrev_b32_e32 v150, 16, v3
	v_and_b32_e32 v151, 0xffff0000, v3
	v_mul_f32_e32 v142, v150, v142
	v_mul_f32_e32 v143, v151, v143
	v_lshlrev_b32_e32 v150, 16, v4
	v_and_b32_e32 v151, 0xffff0000, v4
	v_mul_f32_e32 v144, v150, v144
	v_mul_f32_e32 v145, v151, v145
	v_lshlrev_b32_e32 v150, 16, v5
	v_and_b32_e32 v151, 0xffff0000, v5
	v_mul_f32_e32 v146, v150, v146
	v_mul_f32_e32 v147, v151, v147
	v_mul_f32_e32 v148, v140, v140
	v_fmac_f32_e32 v148, v141, v141
	v_fmac_f32_e32 v148, v142, v142
	v_fmac_f32_e32 v148, v143, v143
	v_fmac_f32_e32 v148, v144, v144
	v_fmac_f32_e32 v148, v145, v145
	v_fmac_f32_e32 v148, v146, v146
	v_fmac_f32_e32 v148, v147, v147
	v_mad_i64_i32 v[152:153], vcc, s41, v221, v[58:59]
	s_add_u32 s41, s41, 1
	global_load_dwordx4 v[2:5], v[152:153], off offset:1536
	global_load_dwordx4 v[18:21], v[152:153], off offset:2560
	s_nop 1
	v_add_f32_dpp v148, v148, v148 quad_perm:[1,0,3,2] row_mask:0xf bank_mask:0xf
	s_nop 1
	v_add_f32_dpp v148, v148, v148 quad_perm:[2,3,0,1] row_mask:0xf bank_mask:0xf
	s_nop 1
	v_add_f32_dpp v148, v148, v148 row_half_mirror row_mask:0xf bank_mask:0xf
	s_nop 1
	v_add_f32_dpp v148, v148, v148 row_mirror row_mask:0xf bank_mask:0xf
	s_nop 1
	v_add_f32_dpp v148, v148, v148 row_bcast:15 row_mask:0xa bank_mask:0xf
	s_nop 1
	v_add_f32_dpp v148, v148, v148 row_bcast:31 row_mask:0xc bank_mask:0xf
	s_nop 0
	v_readlane_b32 s0, v148, 63
	s_nop 1
	v_mov_b32_e32 v148, s0
	v_fmamk_f32 v148, v148, 0x3b000000, v162
	v_mul_f32_e32 v150, 0x4b800000, v148
	v_cmp_gt_f32_e32 vcc, s31, v148
	s_nop 1
	v_cndmask_b32_e32 v148, v148, v150, vcc
	v_rsq_f32_e32 v148, v148
	s_nop 0
	v_mul_f32_e32 v150, 0x45800000, v148
	v_cndmask_b32_e32 v149, v148, v150, vcc
	v_mul_f32_e32 v140, v149, v140
	v_mul_f32_e32 v141, v149, v141
	v_mul_f32_e32 v142, v149, v142
	v_mul_f32_e32 v143, v149, v143
	v_mul_f32_e32 v144, v149, v144
	v_mul_f32_e32 v145, v149, v145
	v_mul_f32_e32 v146, v149, v146
	v_mul_f32_e32 v147, v149, v147
	v_cvt_pk_bf16_f32 v140, v140, v141
	v_cvt_pk_bf16_f32 v141, v142, v143
	v_cvt_pk_bf16_f32 v142, v144, v145
	v_cvt_pk_bf16_f32 v143, v146, v147
	global_store_dwordx4 v[156:157], v[140:143], off sc1
	s_waitcnt vmcnt(10)
; __device__ __forceinline__ float bf_lo(unsigned w) { return __uint_as_float(w << 16); }
; __global__ void __launch_bounds__(512, 2) trunk_fwd(Args args) {
;     ...
;             for (int ch = gw; ch < M / 16; ch += NGW) {
;                 const int r0 = ch * 16, t0 = r0 & (SEQ - 1), c0 = lane * 8;
;                 float w0[8], w1[8], w2[8], u1[8], u2[8];
; #pragma unroll
;                 for (int i = 0; i < 8; ++i) { w0[i] = cw[c0 + i]; w1[i] = cw[512 + c0 + i]; w2[i] = cw[1024 + c0 + i]; u1[i] = 0.f; u2[i] = 0.f; }
;                 if (t0 != 0) {
;                     const u32x4 c1 = *(const u32x4*)(Z + (size_t)(r0 - 1) * INP + 1280 + c0), c2 = *(const u32x4*)(Z + (size_t)(r0 - 2) * INP + 1280 + c0);
; #pragma unroll
;                     for (int i = 0; i < 4; ++i) { u1[2 * i] = bf_lo(c1[i]); u1[2 * i + 1] = bf_hi(c1[i]); u2[2 * i] = bf_lo(c2[i]); u2[2 * i + 1] = bf_hi(c2[i]); }
;                 }
;                 u32x4 gb_n = *(const u32x4*)(Z + (size_t)r0 * INP + 768 + c0), gu_n = *(const u32x4*)(Z + (size_t)r0 * INP + 1280 + c0);
;                 f32x4 pv_n = *(const f32x4*)(pl + (size_t)r0 * PLE + lane * 4);
; #pragma nounroll
;                 for (int rr = 0; rr < 16; ++rr) {
;                     const int r = r0 + rr;
;                     const u32x4 gb = gb_n, gu = gu_n; const f32x4 pv4 = pv_n;
;                     if (rr < 15) { gb_n = *(const u32x4*)(Z + (size_t)(r + 1) * INP + 768 + c0); gu_n = *(const u32x4*)(Z + (size_t)(r + 1) * INP + 1280 + c0);
;                                    pv_n = *(const f32x4*)(pl + (size_t)(r + 1) * PLE + lane * 4); }
;                     float cv[8], uu[8]; float ss = 0.f;
; #pragma unroll
;                     for (int i = 0; i < 4; ++i) {
;                         uu[2 * i] = bf_lo(gu[i]); uu[2 * i + 1] = bf_hi(gu[i]);
;                         cv[2 * i] = bf_lo(gb[i]) * (w0[2 * i] * uu[2 * i] + w1[2 * i] * u1[2 * i] + w2[2 * i] * u2[2 * i]);
;                         cv[2 * i + 1] = bf_hi(gb[i]) * (w0[2 * i + 1] * uu[2 * i + 1] + w1[2 * i + 1] * u1[2 * i + 1] + w2[2 * i + 1] * u2[2 * i + 1]);
;                     }
; #pragma unroll
;                     for (int i = 0; i < 8; ++i) { ss += cv[i] * cv[i]; u2[i] = u1[i]; u1[i] = uu[i]; }
;                     ss = wave_sum(ss);
;                     const float rc = rsqrtf(ss * (1.0f / 512.0f) + EPS);
;                     u32x4 oc;
; #pragma unroll
	v_lshlrev_b32_e32 v204, 16, v22
	v_and_b32_e32 v205, 0xffff0000, v22
	v_lshlrev_b32_e32 v206, 16, v23
	v_and_b32_e32 v207, 0xffff0000, v23
	v_lshlrev_b32_e32 v208, 16, v24
	v_and_b32_e32 v209, 0xffff0000, v24
	v_lshlrev_b32_e32 v210, 16, v25
	v_and_b32_e32 v211, 0xffff0000, v25
	v_mul_f32_e32 v140, v164, v204
	v_mul_f32_e32 v141, v165, v205
	v_mul_f32_e32 v142, v166, v206
	v_mul_f32_e32 v143, v167, v207
	v_mul_f32_e32 v144, v168, v208
	v_mul_f32_e32 v145, v169, v209
	v_mul_f32_e32 v146, v170, v210
	v_mul_f32_e32 v147, v171, v211
	v_fmac_f32_e32 v140, v172, v196
	v_fmac_f32_e32 v141, v173, v197
	v_fmac_f32_e32 v142, v174, v198
	v_fmac_f32_e32 v143, v175, v199
	v_fmac_f32_e32 v144, v176, v200
	v_fmac_f32_e32 v145, v177, v201
	v_fmac_f32_e32 v146, v178, v202
	v_fmac_f32_e32 v147, v179, v203
	v_fmac_f32_e32 v140, v180, v188
	v_fmac_f32_e32 v141, v181, v189
	v_fmac_f32_e32 v142, v182, v190
	v_fmac_f32_e32 v143, v183, v191
	v_fmac_f32_e32 v144, v184, v192
	v_fmac_f32_e32 v145, v185, v193
	v_fmac_f32_e32 v146, v186, v194
	v_fmac_f32_e32 v147, v187, v195
	v_lshlrev_b32_e32 v150, 16, v6
	v_and_b32_e32 v151, 0xffff0000, v6
	v_mul_f32_e32 v140, v150, v140
	v_mul_f32_e32 v141, v151, v141
	v_lshlrev_b32_e32 v150, 16, v7
	v_and_b32_e32 v151, 0xffff0000, v7
	v_mul_f32_e32 v142, v150, v142
	v_mul_f32_e32 v143, v151, v143
	v_lshlrev_b32_e32 v150, 16, v8
	v_and_b32_e32 v151, 0xffff0000, v8
	v_mul_f32_e32 v144, v150, v144
	v_mul_f32_e32 v145, v151, v145
	v_lshlrev_b32_e32 v150, 16, v9
	v_and_b32_e32 v151, 0xffff0000, v9
	v_mul_f32_e32 v146, v150, v146
	v_mul_f32_e32 v147, v151, v147
	v_mul_f32_e32 v148, v140, v140
	v_fmac_f32_e32 v148, v141, v141
	v_fmac_f32_e32 v148, v142, v142
	v_fmac_f32_e32 v148, v143, v143
	v_fmac_f32_e32 v148, v144, v144
	v_fmac_f32_e32 v148, v145, v145
	v_fmac_f32_e32 v148, v146, v146
	v_fmac_f32_e32 v148, v147, v147
	v_mad_i64_i32 v[152:153], vcc, s41, v221, v[58:59]
	s_add_u32 s41, s41, 1
	global_load_dwordx4 v[6:9], v[152:153], off offset:1536
	global_load_dwordx4 v[22:25], v[152:153], off offset:2560
	s_nop 1
	v_add_f32_dpp v148, v148, v148 quad_perm:[1,0,3,2] row_mask:0xf bank_mask:0xf
	s_nop 1
	v_add_f32_dpp v148, v148, v148 quad_perm:[2,3,0,1] row_mask:0xf bank_mask:0xf
	s_nop 1
	v_add_f32_dpp v148, v148, v148 row_half_mirror row_mask:0xf bank_mask:0xf
	s_nop 1
	v_add_f32_dpp v148, v148, v148 row_mirror row_mask:0xf bank_mask:0xf
	s_nop 1
	v_add_f32_dpp v148, v148, v148 row_bcast:15 row_mask:0xa bank_mask:0xf
	s_nop 1
	v_add_f32_dpp v148, v148, v148 row_bcast:31 row_mask:0xc bank_mask:0xf
	s_nop 0
	v_readlane_b32 s0, v148, 63
	s_nop 1
	v_mov_b32_e32 v148, s0
	v_fmamk_f32 v148, v148, 0x3b000000, v162
	v_mul_f32_e32 v150, 0x4b800000, v148
	v_cmp_gt_f32_e32 vcc, s31, v148
	s_nop 1
	v_cndmask_b32_e32 v148, v148, v150, vcc
	v_rsq_f32_e32 v148, v148
	s_nop 0
	v_mul_f32_e32 v150, 0x45800000, v148
	v_cndmask_b32_e32 v149, v148, v150, vcc
	v_mul_f32_e32 v140, v149, v140
	v_mul_f32_e32 v141, v149, v141
	v_mul_f32_e32 v142, v149, v142
	v_mul_f32_e32 v143, v149, v143
	v_mul_f32_e32 v144, v149, v144
	v_mul_f32_e32 v145, v149, v145
	v_mul_f32_e32 v146, v149, v146
	v_mul_f32_e32 v147, v149, v147
	v_cvt_pk_bf16_f32 v140, v140, v141
	v_cvt_pk_bf16_f32 v141, v142, v143
	v_cvt_pk_bf16_f32 v142, v144, v145
	v_cvt_pk_bf16_f32 v143, v146, v147
	global_store_dwordx4 v[156:157], v[140:143], off offset:2048 sc1
	v_lshl_add_u64 v[156:157], v[156:157], 0, s[20:21]
	s_waitcnt vmcnt(10)
	v_lshlrev_b32_e32 v188, 16, v26
	v_and_b32_e32 v189, 0xffff0000, v26
	v_lshlrev_b32_e32 v190, 16, v27
	v_and_b32_e32 v191, 0xffff0000, v27
	v_lshlrev_b32_e32 v192, 16, v28
	v_and_b32_e32 v193, 0xffff0000, v28
	v_lshlrev_b32_e32 v194, 16, v29
	v_and_b32_e32 v195, 0xffff0000, v29
	v_mul_f32_e32 v140, v164, v188
	v_mul_f32_e32 v141, v165, v189
	v_mul_f32_e32 v142, v166, v190
	v_mul_f32_e32 v143, v167, v191
	v_mul_f32_e32 v144, v168, v192
	v_mul_f32_e32 v145, v169, v193
	v_mul_f32_e32 v146, v170, v194
	v_mul_f32_e32 v147, v171, v195
	v_fmac_f32_e32 v140, v172, v204
	v_fmac_f32_e32 v141, v173, v205
	v_fmac_f32_e32 v142, v174, v206
	v_fmac_f32_e32 v143, v175, v207
	v_fmac_f32_e32 v144, v176, v208
	v_fmac_f32_e32 v145, v177, v209
	v_fmac_f32_e32 v146, v178, v210
	v_fmac_f32_e32 v147, v179, v211
	v_fmac_f32_e32 v140, v180, v196
	v_fmac_f32_e32 v141, v181, v197
	v_fmac_f32_e32 v142, v182, v198
	v_fmac_f32_e32 v143, v183, v199
	v_fmac_f32_e32 v144, v184, v200
	v_fmac_f32_e32 v145, v185, v201
	v_fmac_f32_e32 v146, v186, v202
	v_fmac_f32_e32 v147, v187, v203
	v_lshlrev_b32_e32 v150, 16, v10
	v_and_b32_e32 v151, 0xffff0000, v10
	v_mul_f32_e32 v140, v150, v140
	v_mul_f32_e32 v141, v151, v141
	v_lshlrev_b32_e32 v150, 16, v11
	v_and_b32_e32 v151, 0xffff0000, v11
	v_mul_f32_e32 v142, v150, v142
	v_mul_f32_e32 v143, v151, v143
	v_lshlrev_b32_e32 v150, 16, v12
	v_and_b32_e32 v151, 0xffff0000, v12
	v_mul_f32_e32 v144, v150, v144
	v_mul_f32_e32 v145, v151, v145
	v_lshlrev_b32_e32 v150, 16, v13
	v_and_b32_e32 v151, 0xffff0000, v13
	v_mul_f32_e32 v146, v150, v146
	v_mul_f32_e32 v147, v151, v147
	v_mul_f32_e32 v148, v140, v140
	v_fmac_f32_e32 v148, v141, v141
	v_fmac_f32_e32 v148, v142, v142
	v_fmac_f32_e32 v148, v143, v143
	v_fmac_f32_e32 v148, v144, v144
	v_fmac_f32_e32 v148, v145, v145
	v_fmac_f32_e32 v148, v146, v146
	v_fmac_f32_e32 v148, v147, v147
	v_mad_i64_i32 v[152:153], vcc, s41, v221, v[58:59]
	s_add_u32 s41, s41, 1
	global_load_dwordx4 v[10:13], v[152:153], off offset:1536
	global_load_dwordx4 v[26:29], v[152:153], off offset:2560
	s_nop 1
	v_add_f32_dpp v148, v148, v148 quad_perm:[1,0,3,2] row_mask:0xf bank_mask:0xf
	s_nop 1
	v_add_f32_dpp v148, v148, v148 quad_perm:[2,3,0,1] row_mask:0xf bank_mask:0xf
	s_nop 1
	v_add_f32_dpp v148, v148, v148 row_half_mirror row_mask:0xf bank_mask:0xf
	s_nop 1
	v_add_f32_dpp v148, v148, v148 row_mirror row_mask:0xf bank_mask:0xf
	s_nop 1
	v_add_f32_dpp v148, v148, v148 row_bcast:15 row_mask:0xa bank_mask:0xf
	s_nop 1
	v_add_f32_dpp v148, v148, v148 row_bcast:31 row_mask:0xc bank_mask:0xf
	s_nop 0
	v_readlane_b32 s0, v148, 63
	s_nop 1
	v_mov_b32_e32 v148, s0
	v_fmamk_f32 v148, v148, 0x3b000000, v162
	v_mul_f32_e32 v150, 0x4b800000, v148
	v_cmp_gt_f32_e32 vcc, s31, v148
	s_nop 1
	v_cndmask_b32_e32 v148, v148, v150, vcc
	v_rsq_f32_e32 v148, v148
	s_nop 0
	v_mul_f32_e32 v150, 0x45800000, v148
	v_cndmask_b32_e32 v149, v148, v150, vcc
	v_mul_f32_e32 v140, v149, v140
	v_mul_f32_e32 v141, v149, v141
	v_mul_f32_e32 v142, v149, v142
	v_mul_f32_e32 v143, v149, v143
	v_mul_f32_e32 v144, v149, v144
	v_mul_f32_e32 v145, v149, v145
	v_mul_f32_e32 v146, v149, v146
	v_mul_f32_e32 v147, v149, v147
	v_cvt_pk_bf16_f32 v140, v140, v141
	v_cvt_pk_bf16_f32 v141, v142, v143
	v_cvt_pk_bf16_f32 v142, v144, v145
	v_cvt_pk_bf16_f32 v143, v146, v147
	global_store_dwordx4 v[156:157], v[140:143], off sc1
	s_waitcnt vmcnt(10)
; __device__ __forceinline__ float bf_lo(unsigned w) { return __uint_as_float(w << 16); }
; __global__ void __launch_bounds__(512, 2) trunk_fwd(Args args) {
;     ...
;             for (int ch = gw; ch < M / 16; ch += NGW) {
;                 const int r0 = ch * 16, t0 = r0 & (SEQ - 1), c0 = lane * 8;
;                 float w0[8], w1[8], w2[8], u1[8], u2[8];
; #pragma unroll
;                 for (int i = 0; i < 8; ++i) { w0[i] = cw[c0 + i]; w1[i] = cw[512 + c0 + i]; w2[i] = cw[1024 + c0 + i]; u1[i] = 0.f; u2[i] = 0.f; }
;                 if (t0 != 0) {
;                     const u32x4 c1 = *(const u32x4*)(Z + (size_t)(r0 - 1) * INP + 1280 + c0), c2 = *(const u32x4*)(Z + (size_t)(r0 - 2) * INP + 1280 + c0);
; #pragma unroll
;                     for (int i = 0; i < 4; ++i) { u1[2 * i] = bf_lo(c1[i]); u1[2 * i + 1] = bf_hi(c1[i]); u2[2 * i] = bf_lo(c2[i]); u2[2 * i + 1] = bf_hi(c2[i]); }
;                 }
;                 u32x4 gb_n = *(const u32x4*)(Z + (size_t)r0 * INP + 768 + c0), gu_n = *(const u32x4*)(Z + (size_t)r0 * INP + 1280 + c0);
;                 f32x4 pv_n = *(const f32x4*)(pl + (size_t)r0 * PLE + lane * 4);
; #pragma nounroll
;                 for (int rr = 0; rr < 16; ++rr) {
;                     const int r = r0 + rr;
;                     const u32x4 gb = gb_n, gu = gu_n; const f32x4 pv4 = pv_n;
;                     if (rr < 15) { gb_n = *(const u32x4*)(Z + (size_t)(r + 1) * INP + 768 + c0); gu_n = *(const u32x4*)(Z + (size_t)(r + 1) * INP + 1280 + c0);
;                                    pv_n = *(const f32x4*)(pl + (size_t)(r + 1) * PLE + lane * 4); }
;                     float cv[8], uu[8]; float ss = 0.f;
; #pragma unroll
;                     for (int i = 0; i < 4; ++i) {
;                         uu[2 * i] = bf_lo(gu[i]); uu[2 * i + 1] = bf_hi(gu[i]);
;                         cv[2 * i] = bf_lo(gb[i]) * (w0[2 * i] * uu[2 * i] + w1[2 * i] * u1[2 * i] + w2[2 * i] * u2[2 * i]);
;                         cv[2 * i + 1] = bf_hi(gb[i]) * (w0[2 * i + 1] * uu[2 * i + 1] + w1[2 * i + 1] * u1[2 * i + 1] + w2[2 * i + 1] * u2[2 * i + 1]);
;                     }
; #pragma unroll
;                     for (int i = 0; i < 8; ++i) { ss += cv[i] * cv[i]; u2[i] = u1[i]; u1[i] = uu[i]; }
;                     ss = wave_sum(ss);
;                     const float rc = rsqrtf(ss * (1.0f / 512.0f) + EPS);
;                     u32x4 oc;
; #pragma unroll
	v_lshlrev_b32_e32 v196, 16, v30
	v_and_b32_e32 v197, 0xffff0000, v30
	v_lshlrev_b32_e32 v198, 16, v31
	v_and_b32_e32 v199, 0xffff0000, v31
	v_lshlrev_b32_e32 v200, 16, v32
	v_and_b32_e32 v201, 0xffff0000, v32
	v_lshlrev_b32_e32 v202, 16, v33
	v_and_b32_e32 v203, 0xffff0000, v33
	v_mul_f32_e32 v140, v164, v196
	v_mul_f32_e32 v141, v165, v197
	v_mul_f32_e32 v142, v166, v198
	v_mul_f32_e32 v143, v167, v199
	v_mul_f32_e32 v144, v168, v200
	v_mul_f32_e32 v145, v169, v201
	v_mul_f32_e32 v146, v170, v202
	v_mul_f32_e32 v147, v171, v203
	v_fmac_f32_e32 v140, v172, v188
	v_fmac_f32_e32 v141, v173, v189
	v_fmac_f32_e32 v142, v174, v190
	v_fmac_f32_e32 v143, v175, v191
	v_fmac_f32_e32 v144, v176, v192
	v_fmac_f32_e32 v145, v177, v193
	v_fmac_f32_e32 v146, v178, v194
	v_fmac_f32_e32 v147, v179, v195
	v_fmac_f32_e32 v140, v180, v204
	v_fmac_f32_e32 v141, v181, v205
	v_fmac_f32_e32 v142, v182, v206
	v_fmac_f32_e32 v143, v183, v207
	v_fmac_f32_e32 v144, v184, v208
	v_fmac_f32_e32 v145, v185, v209
	v_fmac_f32_e32 v146, v186, v210
	v_fmac_f32_e32 v147, v187, v211
	v_lshlrev_b32_e32 v150, 16, v14
	v_and_b32_e32 v151, 0xffff0000, v14
	v_mul_f32_e32 v140, v150, v140
	v_mul_f32_e32 v141, v151, v141
	v_lshlrev_b32_e32 v150, 16, v15
	v_and_b32_e32 v151, 0xffff0000, v15
	v_mul_f32_e32 v142, v150, v142
	v_mul_f32_e32 v143, v151, v143
	v_lshlrev_b32_e32 v150, 16, v16
	v_and_b32_e32 v151, 0xffff0000, v16
	v_mul_f32_e32 v144, v150, v144
	v_mul_f32_e32 v145, v151, v145
	v_lshlrev_b32_e32 v150, 16, v17
	v_and_b32_e32 v151, 0xffff0000, v17
	v_mul_f32_e32 v146, v150, v146
	v_mul_f32_e32 v147, v151, v147
	v_mul_f32_e32 v148, v140, v140
	v_fmac_f32_e32 v148, v141, v141
	v_fmac_f32_e32 v148, v142, v142
	v_fmac_f32_e32 v148, v143, v143
	v_fmac_f32_e32 v148, v144, v144
	v_fmac_f32_e32 v148, v145, v145
	v_fmac_f32_e32 v148, v146, v146
	v_fmac_f32_e32 v148, v147, v147
	v_mad_i64_i32 v[152:153], vcc, s41, v221, v[58:59]
	s_add_u32 s41, s41, 1
	global_load_dwordx4 v[14:17], v[152:153], off offset:1536
	global_load_dwordx4 v[30:33], v[152:153], off offset:2560
	s_nop 1
	v_add_f32_dpp v148, v148, v148 quad_perm:[1,0,3,2] row_mask:0xf bank_mask:0xf
	s_nop 1
	v_add_f32_dpp v148, v148, v148 quad_perm:[2,3,0,1] row_mask:0xf bank_mask:0xf
	s_nop 1
	v_add_f32_dpp v148, v148, v148 row_half_mirror row_mask:0xf bank_mask:0xf
	s_nop 1
	v_add_f32_dpp v148, v148, v148 row_mirror row_mask:0xf bank_mask:0xf
	s_nop 1
	v_add_f32_dpp v148, v148, v148 row_bcast:15 row_mask:0xa bank_mask:0xf
	s_nop 1
	v_add_f32_dpp v148, v148, v148 row_bcast:31 row_mask:0xc bank_mask:0xf
	s_nop 0
	v_readlane_b32 s0, v148, 63
	s_nop 1
	v_mov_b32_e32 v148, s0
	v_fmamk_f32 v148, v148, 0x3b000000, v162
	v_mul_f32_e32 v150, 0x4b800000, v148
	v_cmp_gt_f32_e32 vcc, s31, v148
	s_nop 1
	v_cndmask_b32_e32 v148, v148, v150, vcc
	v_rsq_f32_e32 v148, v148
	s_nop 0
	v_mul_f32_e32 v150, 0x45800000, v148
	v_cndmask_b32_e32 v149, v148, v150, vcc
	v_mul_f32_e32 v140, v149, v140
	v_mul_f32_e32 v141, v149, v141
	v_mul_f32_e32 v142, v149, v142
	v_mul_f32_e32 v143, v149, v143
	v_mul_f32_e32 v144, v149, v144
	v_mul_f32_e32 v145, v149, v145
	v_mul_f32_e32 v146, v149, v146
	v_mul_f32_e32 v147, v149, v147
	v_cvt_pk_bf16_f32 v140, v140, v141
	v_cvt_pk_bf16_f32 v141, v142, v143
	v_cvt_pk_bf16_f32 v142, v144, v145
	v_cvt_pk_bf16_f32 v143, v146, v147
	global_store_dwordx4 v[156:157], v[140:143], off offset:2048 sc1
	v_lshl_add_u64 v[156:157], v[156:157], 0, s[20:21]
	s_waitcnt vmcnt(10)
	v_lshlrev_b32_e32 v204, 16, v18
	v_and_b32_e32 v205, 0xffff0000, v18
	v_lshlrev_b32_e32 v206, 16, v19
	v_and_b32_e32 v207, 0xffff0000, v19
	v_lshlrev_b32_e32 v208, 16, v20
	v_and_b32_e32 v209, 0xffff0000, v20
	v_lshlrev_b32_e32 v210, 16, v21
	v_and_b32_e32 v211, 0xffff0000, v21
	v_mul_f32_e32 v140, v164, v204
	v_mul_f32_e32 v141, v165, v205
	v_mul_f32_e32 v142, v166, v206
	v_mul_f32_e32 v143, v167, v207
	v_mul_f32_e32 v144, v168, v208
	v_mul_f32_e32 v145, v169, v209
	v_mul_f32_e32 v146, v170, v210
	v_mul_f32_e32 v147, v171, v211
	v_fmac_f32_e32 v140, v172, v196
	v_fmac_f32_e32 v141, v173, v197
	v_fmac_f32_e32 v142, v174, v198
	v_fmac_f32_e32 v143, v175, v199
	v_fmac_f32_e32 v144, v176, v200
	v_fmac_f32_e32 v145, v177, v201
	v_fmac_f32_e32 v146, v178, v202
	v_fmac_f32_e32 v147, v179, v203
	v_fmac_f32_e32 v140, v180, v188
	v_fmac_f32_e32 v141, v181, v189
	v_fmac_f32_e32 v142, v182, v190
	v_fmac_f32_e32 v143, v183, v191
	v_fmac_f32_e32 v144, v184, v192
	v_fmac_f32_e32 v145, v185, v193
	v_fmac_f32_e32 v146, v186, v194
	v_fmac_f32_e32 v147, v187, v195
	v_lshlrev_b32_e32 v150, 16, v2
	v_and_b32_e32 v151, 0xffff0000, v2
	v_mul_f32_e32 v140, v150, v140
	v_mul_f32_e32 v141, v151, v141
	v_lshlrev_b32_e32 v150, 16, v3
	v_and_b32_e32 v151, 0xffff0000, v3
	v_mul_f32_e32 v142, v150, v142
	v_mul_f32_e32 v143, v151, v143
	v_lshlrev_b32_e32 v150, 16, v4
	v_and_b32_e32 v151, 0xffff0000, v4
	v_mul_f32_e32 v144, v150, v144
	v_mul_f32_e32 v145, v151, v145
	v_lshlrev_b32_e32 v150, 16, v5
	v_and_b32_e32 v151, 0xffff0000, v5
	v_mul_f32_e32 v146, v150, v146
	v_mul_f32_e32 v147, v151, v147
	v_mul_f32_e32 v148, v140, v140
	v_fmac_f32_e32 v148, v141, v141
	v_fmac_f32_e32 v148, v142, v142
	v_fmac_f32_e32 v148, v143, v143
	v_fmac_f32_e32 v148, v144, v144
	v_fmac_f32_e32 v148, v145, v145
	v_fmac_f32_e32 v148, v146, v146
	v_fmac_f32_e32 v148, v147, v147
	v_mad_i64_i32 v[152:153], vcc, s41, v221, v[58:59]
	s_add_u32 s41, s41, 1
	global_load_dwordx4 v[2:5], v[152:153], off offset:1536
	global_load_dwordx4 v[18:21], v[152:153], off offset:2560
	s_nop 1
	v_add_f32_dpp v148, v148, v148 quad_perm:[1,0,3,2] row_mask:0xf bank_mask:0xf
	s_nop 1
	v_add_f32_dpp v148, v148, v148 quad_perm:[2,3,0,1] row_mask:0xf bank_mask:0xf
	s_nop 1
	v_add_f32_dpp v148, v148, v148 row_half_mirror row_mask:0xf bank_mask:0xf
	s_nop 1
	v_add_f32_dpp v148, v148, v148 row_mirror row_mask:0xf bank_mask:0xf
	s_nop 1
	v_add_f32_dpp v148, v148, v148 row_bcast:15 row_mask:0xa bank_mask:0xf
	s_nop 1
	v_add_f32_dpp v148, v148, v148 row_bcast:31 row_mask:0xc bank_mask:0xf
	s_nop 0
	v_readlane_b32 s0, v148, 63
	s_nop 1
	v_mov_b32_e32 v148, s0
	v_fmamk_f32 v148, v148, 0x3b000000, v162
	v_mul_f32_e32 v150, 0x4b800000, v148
	v_cmp_gt_f32_e32 vcc, s31, v148
	s_nop 1
	v_cndmask_b32_e32 v148, v148, v150, vcc
	v_rsq_f32_e32 v148, v148
	s_nop 0
	v_mul_f32_e32 v150, 0x45800000, v148
	v_cndmask_b32_e32 v149, v148, v150, vcc
	v_mul_f32_e32 v140, v149, v140
	v_mul_f32_e32 v141, v149, v141
	v_mul_f32_e32 v142, v149, v142
	v_mul_f32_e32 v143, v149, v143
	v_mul_f32_e32 v144, v149, v144
	v_mul_f32_e32 v145, v149, v145
	v_mul_f32_e32 v146, v149, v146
	v_mul_f32_e32 v147, v149, v147
	v_cvt_pk_bf16_f32 v140, v140, v141
	v_cvt_pk_bf16_f32 v141, v142, v143
	v_cvt_pk_bf16_f32 v142, v144, v145
	v_cvt_pk_bf16_f32 v143, v146, v147
	global_store_dwordx4 v[156:157], v[140:143], off sc1
	s_waitcnt vmcnt(10)
; __device__ __forceinline__ float bf_lo(unsigned w) { return __uint_as_float(w << 16); }
; __global__ void __launch_bounds__(512, 2) trunk_fwd(Args args) {
;     ...
;             for (int ch = gw; ch < M / 16; ch += NGW) {
;                 const int r0 = ch * 16, t0 = r0 & (SEQ - 1), c0 = lane * 8;
;                 float w0[8], w1[8], w2[8], u1[8], u2[8];
; #pragma unroll
;                 for (int i = 0; i < 8; ++i) { w0[i] = cw[c0 + i]; w1[i] = cw[512 + c0 + i]; w2[i] = cw[1024 + c0 + i]; u1[i] = 0.f; u2[i] = 0.f; }
;                 if (t0 != 0) {
;                     const u32x4 c1 = *(const u32x4*)(Z + (size_t)(r0 - 1) * INP + 1280 + c0), c2 = *(const u32x4*)(Z + (size_t)(r0 - 2) * INP + 1280 + c0);
; #pragma unroll
;                     for (int i = 0; i < 4; ++i) { u1[2 * i] = bf_lo(c1[i]); u1[2 * i + 1] = bf_hi(c1[i]); u2[2 * i] = bf_lo(c2[i]); u2[2 * i + 1] = bf_hi(c2[i]); }
;                 }
;                 u32x4 gb_n = *(const u32x4*)(Z + (size_t)r0 * INP + 768 + c0), gu_n = *(const u32x4*)(Z + (size_t)r0 * INP + 1280 + c0);
;                 f32x4 pv_n = *(const f32x4*)(pl + (size_t)r0 * PLE + lane * 4);
; #pragma nounroll
;                 for (int rr = 0; rr < 16; ++rr) {
;                     const int r = r0 + rr;
;                     const u32x4 gb = gb_n, gu = gu_n; const f32x4 pv4 = pv_n;
;                     if (rr < 15) { gb_n = *(const u32x4*)(Z + (size_t)(r + 1) * INP + 768 + c0); gu_n = *(const u32x4*)(Z + (size_t)(r + 1) * INP + 1280 + c0);
;                                    pv_n = *(const f32x4*)(pl + (size_t)(r + 1) * PLE + lane * 4); }
;                     float cv[8], uu[8]; float ss = 0.f;
; #pragma unroll
;                     for (int i = 0; i < 4; ++i) {
;                         uu[2 * i] = bf_lo(gu[i]); uu[2 * i + 1] = bf_hi(gu[i]);
;                         cv[2 * i] = bf_lo(gb[i]) * (w0[2 * i] * uu[2 * i] + w1[2 * i] * u1[2 * i] + w2[2 * i] * u2[2 * i]);
;                         cv[2 * i + 1] = bf_hi(gb[i]) * (w0[2 * i + 1] * uu[2 * i + 1] + w1[2 * i + 1] * u1[2 * i + 1] + w2[2 * i + 1] * u2[2 * i + 1]);
;                     }
; #pragma unroll
;                     for (int i = 0; i < 8; ++i) { ss += cv[i] * cv[i]; u2[i] = u1[i]; u1[i] = uu[i]; }
;                     ss = wave_sum(ss);
;                     const float rc = rsqrtf(ss * (1.0f / 512.0f) + EPS);
;                     u32x4 oc;
; #pragma unroll
	v_lshlrev_b32_e32 v188, 16, v22
	v_and_b32_e32 v189, 0xffff0000, v22
	v_lshlrev_b32_e32 v190, 16, v23
	v_and_b32_e32 v191, 0xffff0000, v23
	v_lshlrev_b32_e32 v192, 16, v24
	v_and_b32_e32 v193, 0xffff0000, v24
	v_lshlrev_b32_e32 v194, 16, v25
	v_and_b32_e32 v195, 0xffff0000, v25
	v_mul_f32_e32 v140, v164, v188
	v_mul_f32_e32 v141, v165, v189
	v_mul_f32_e32 v142, v166, v190
	v_mul_f32_e32 v143, v167, v191
	v_mul_f32_e32 v144, v168, v192
	v_mul_f32_e32 v145, v169, v193
	v_mul_f32_e32 v146, v170, v194
	v_mul_f32_e32 v147, v171, v195
	v_fmac_f32_e32 v140, v172, v204
	v_fmac_f32_e32 v141, v173, v205
	v_fmac_f32_e32 v142, v174, v206
	v_fmac_f32_e32 v143, v175, v207
	v_fmac_f32_e32 v144, v176, v208
	v_fmac_f32_e32 v145, v177, v209
	v_fmac_f32_e32 v146, v178, v210
	v_fmac_f32_e32 v147, v179, v211
	v_fmac_f32_e32 v140, v180, v196
	v_fmac_f32_e32 v141, v181, v197
	v_fmac_f32_e32 v142, v182, v198
	v_fmac_f32_e32 v143, v183, v199
	v_fmac_f32_e32 v144, v184, v200
	v_fmac_f32_e32 v145, v185, v201
	v_fmac_f32_e32 v146, v186, v202
	v_fmac_f32_e32 v147, v187, v203
	v_lshlrev_b32_e32 v150, 16, v6
	v_and_b32_e32 v151, 0xffff0000, v6
	v_mul_f32_e32 v140, v150, v140
	v_mul_f32_e32 v141, v151, v141
	v_lshlrev_b32_e32 v150, 16, v7
	v_and_b32_e32 v151, 0xffff0000, v7
	v_mul_f32_e32 v142, v150, v142
	v_mul_f32_e32 v143, v151, v143
	v_lshlrev_b32_e32 v150, 16, v8
	v_and_b32_e32 v151, 0xffff0000, v8
	v_mul_f32_e32 v144, v150, v144
	v_mul_f32_e32 v145, v151, v145
	v_lshlrev_b32_e32 v150, 16, v9
	v_and_b32_e32 v151, 0xffff0000, v9
	v_mul_f32_e32 v146, v150, v146
	v_mul_f32_e32 v147, v151, v147
	v_mul_f32_e32 v148, v140, v140
	v_fmac_f32_e32 v148, v141, v141
	v_fmac_f32_e32 v148, v142, v142
	v_fmac_f32_e32 v148, v143, v143
	v_fmac_f32_e32 v148, v144, v144
	v_fmac_f32_e32 v148, v145, v145
	v_fmac_f32_e32 v148, v146, v146
	v_fmac_f32_e32 v148, v147, v147
	v_mad_i64_i32 v[152:153], vcc, s41, v221, v[58:59]
	s_add_u32 s41, s41, 1
	global_load_dwordx4 v[6:9], v[152:153], off offset:1536
	global_load_dwordx4 v[22:25], v[152:153], off offset:2560
	s_nop 1
	v_add_f32_dpp v148, v148, v148 quad_perm:[1,0,3,2] row_mask:0xf bank_mask:0xf
	s_nop 1
	v_add_f32_dpp v148, v148, v148 quad_perm:[2,3,0,1] row_mask:0xf bank_mask:0xf
	s_nop 1
	v_add_f32_dpp v148, v148, v148 row_half_mirror row_mask:0xf bank_mask:0xf
	s_nop 1
	v_add_f32_dpp v148, v148, v148 row_mirror row_mask:0xf bank_mask:0xf
	s_nop 1
	v_add_f32_dpp v148, v148, v148 row_bcast:15 row_mask:0xa bank_mask:0xf
	s_nop 1
	v_add_f32_dpp v148, v148, v148 row_bcast:31 row_mask:0xc bank_mask:0xf
	s_nop 0
	v_readlane_b32 s0, v148, 63
	s_nop 1
	v_mov_b32_e32 v148, s0
	v_fmamk_f32 v148, v148, 0x3b000000, v162
	v_mul_f32_e32 v150, 0x4b800000, v148
	v_cmp_gt_f32_e32 vcc, s31, v148
	s_nop 1
	v_cndmask_b32_e32 v148, v148, v150, vcc
	v_rsq_f32_e32 v148, v148
	s_nop 0
	v_mul_f32_e32 v150, 0x45800000, v148
	v_cndmask_b32_e32 v149, v148, v150, vcc
	v_mul_f32_e32 v140, v149, v140
	v_mul_f32_e32 v141, v149, v141
	v_mul_f32_e32 v142, v149, v142
	v_mul_f32_e32 v143, v149, v143
	v_mul_f32_e32 v144, v149, v144
	v_mul_f32_e32 v145, v149, v145
	v_mul_f32_e32 v146, v149, v146
	v_mul_f32_e32 v147, v149, v147
	v_cvt_pk_bf16_f32 v140, v140, v141
	v_cvt_pk_bf16_f32 v141, v142, v143
	v_cvt_pk_bf16_f32 v142, v144, v145
	v_cvt_pk_bf16_f32 v143, v146, v147
	global_store_dwordx4 v[156:157], v[140:143], off offset:2048 sc1
	v_lshl_add_u64 v[156:157], v[156:157], 0, s[20:21]
	s_waitcnt vmcnt(10)
	v_lshlrev_b32_e32 v196, 16, v26
	v_and_b32_e32 v197, 0xffff0000, v26
	v_lshlrev_b32_e32 v198, 16, v27
	v_and_b32_e32 v199, 0xffff0000, v27
	v_lshlrev_b32_e32 v200, 16, v28
	v_and_b32_e32 v201, 0xffff0000, v28
	v_lshlrev_b32_e32 v202, 16, v29
	v_and_b32_e32 v203, 0xffff0000, v29
	v_mul_f32_e32 v140, v164, v196
	v_mul_f32_e32 v141, v165, v197
	v_mul_f32_e32 v142, v166, v198
	v_mul_f32_e32 v143, v167, v199
	v_mul_f32_e32 v144, v168, v200
	v_mul_f32_e32 v145, v169, v201
	v_mul_f32_e32 v146, v170, v202
	v_mul_f32_e32 v147, v171, v203
	v_fmac_f32_e32 v140, v172, v188
	v_fmac_f32_e32 v141, v173, v189
	v_fmac_f32_e32 v142, v174, v190
	v_fmac_f32_e32 v143, v175, v191
	v_fmac_f32_e32 v144, v176, v192
	v_fmac_f32_e32 v145, v177, v193
	v_fmac_f32_e32 v146, v178, v194
	v_fmac_f32_e32 v147, v179, v195
	v_fmac_f32_e32 v140, v180, v204
	v_fmac_f32_e32 v141, v181, v205
	v_fmac_f32_e32 v142, v182, v206
	v_fmac_f32_e32 v143, v183, v207
	v_fmac_f32_e32 v144, v184, v208
	v_fmac_f32_e32 v145, v185, v209
	v_fmac_f32_e32 v146, v186, v210
	v_fmac_f32_e32 v147, v187, v211
	v_lshlrev_b32_e32 v150, 16, v10
	v_and_b32_e32 v151, 0xffff0000, v10
	v_mul_f32_e32 v140, v150, v140
	v_mul_f32_e32 v141, v151, v141
	v_lshlrev_b32_e32 v150, 16, v11
	v_and_b32_e32 v151, 0xffff0000, v11
	v_mul_f32_e32 v142, v150, v142
	v_mul_f32_e32 v143, v151, v143
	v_lshlrev_b32_e32 v150, 16, v12
	v_and_b32_e32 v151, 0xffff0000, v12
	v_mul_f32_e32 v144, v150, v144
	v_mul_f32_e32 v145, v151, v145
	v_lshlrev_b32_e32 v150, 16, v13
	v_and_b32_e32 v151, 0xffff0000, v13
	v_mul_f32_e32 v146, v150, v146
	v_mul_f32_e32 v147, v151, v147
	v_mul_f32_e32 v148, v140, v140
	v_fmac_f32_e32 v148, v141, v141
	v_fmac_f32_e32 v148, v142, v142
	v_fmac_f32_e32 v148, v143, v143
	v_fmac_f32_e32 v148, v144, v144
	v_fmac_f32_e32 v148, v145, v145
	v_fmac_f32_e32 v148, v146, v146
	v_fmac_f32_e32 v148, v147, v147
	v_mad_i64_i32 v[152:153], vcc, s41, v221, v[58:59]
	s_add_u32 s41, s41, 1
	global_load_dwordx4 v[10:13], v[152:153], off offset:1536
	global_load_dwordx4 v[26:29], v[152:153], off offset:2560
	s_nop 1
	v_add_f32_dpp v148, v148, v148 quad_perm:[1,0,3,2] row_mask:0xf bank_mask:0xf
	s_nop 1
	v_add_f32_dpp v148, v148, v148 quad_perm:[2,3,0,1] row_mask:0xf bank_mask:0xf
	s_nop 1
	v_add_f32_dpp v148, v148, v148 row_half_mirror row_mask:0xf bank_mask:0xf
	s_nop 1
	v_add_f32_dpp v148, v148, v148 row_mirror row_mask:0xf bank_mask:0xf
	s_nop 1
	v_add_f32_dpp v148, v148, v148 row_bcast:15 row_mask:0xa bank_mask:0xf
	s_nop 1
	v_add_f32_dpp v148, v148, v148 row_bcast:31 row_mask:0xc bank_mask:0xf
	s_nop 0
	v_readlane_b32 s0, v148, 63
	s_nop 1
	v_mov_b32_e32 v148, s0
	v_fmamk_f32 v148, v148, 0x3b000000, v162
	v_mul_f32_e32 v150, 0x4b800000, v148
	v_cmp_gt_f32_e32 vcc, s31, v148
	s_nop 1
	v_cndmask_b32_e32 v148, v148, v150, vcc
	v_rsq_f32_e32 v148, v148
	s_nop 0
	v_mul_f32_e32 v150, 0x45800000, v148
	v_cndmask_b32_e32 v149, v148, v150, vcc
	v_mul_f32_e32 v140, v149, v140
	v_mul_f32_e32 v141, v149, v141
	v_mul_f32_e32 v142, v149, v142
	v_mul_f32_e32 v143, v149, v143
	v_mul_f32_e32 v144, v149, v144
	v_mul_f32_e32 v145, v149, v145
	v_mul_f32_e32 v146, v149, v146
	v_mul_f32_e32 v147, v149, v147
	v_cvt_pk_bf16_f32 v140, v140, v141
	v_cvt_pk_bf16_f32 v141, v142, v143
	v_cvt_pk_bf16_f32 v142, v144, v145
	v_cvt_pk_bf16_f32 v143, v146, v147
	global_store_dwordx4 v[156:157], v[140:143], off sc1
	s_waitcnt vmcnt(10)
; __device__ __forceinline__ float bf_lo(unsigned w) { return __uint_as_float(w << 16); }
; __global__ void __launch_bounds__(512, 2) trunk_fwd(Args args) {
;     ...
;             for (int ch = gw; ch < M / 16; ch += NGW) {
;                 const int r0 = ch * 16, t0 = r0 & (SEQ - 1), c0 = lane * 8;
;                 float w0[8], w1[8], w2[8], u1[8], u2[8];
; #pragma unroll
;                 for (int i = 0; i < 8; ++i) { w0[i] = cw[c0 + i]; w1[i] = cw[512 + c0 + i]; w2[i] = cw[1024 + c0 + i]; u1[i] = 0.f; u2[i] = 0.f; }
;                 if (t0 != 0) {
;                     const u32x4 c1 = *(const u32x4*)(Z + (size_t)(r0 - 1) * INP + 1280 + c0), c2 = *(const u32x4*)(Z + (size_t)(r0 - 2) * INP + 1280 + c0);
; #pragma unroll
;                     for (int i = 0; i < 4; ++i) { u1[2 * i] = bf_lo(c1[i]); u1[2 * i + 1] = bf_hi(c1[i]); u2[2 * i] = bf_lo(c2[i]); u2[2 * i + 1] = bf_hi(c2[i]); }
;                 }
;                 u32x4 gb_n = *(const u32x4*)(Z + (size_t)r0 * INP + 768 + c0), gu_n = *(const u32x4*)(Z + (size_t)r0 * INP + 1280 + c0);
;                 f32x4 pv_n = *(const f32x4*)(pl + (size_t)r0 * PLE + lane * 4);
; #pragma nounroll
;                 for (int rr = 0; rr < 16; ++rr) {
;                     const int r = r0 + rr;
;                     const u32x4 gb = gb_n, gu = gu_n; const f32x4 pv4 = pv_n;
;                     if (rr < 15) { gb_n = *(const u32x4*)(Z + (size_t)(r + 1) * INP + 768 + c0); gu_n = *(const u32x4*)(Z + (size_t)(r + 1) * INP + 1280 + c0);
;                                    pv_n = *(const f32x4*)(pl + (size_t)(r + 1) * PLE + lane * 4); }
;                     float cv[8], uu[8]; float ss = 0.f;
; #pragma unroll
;                     for (int i = 0; i < 4; ++i) {
;                         uu[2 * i] = bf_lo(gu[i]); uu[2 * i + 1] = bf_hi(gu[i]);
;                         cv[2 * i] = bf_lo(gb[i]) * (w0[2 * i] * uu[2 * i] + w1[2 * i] * u1[2 * i] + w2[2 * i] * u2[2 * i]);
;                         cv[2 * i + 1] = bf_hi(gb[i]) * (w0[2 * i + 1] * uu[2 * i + 1] + w1[2 * i + 1] * u1[2 * i + 1] + w2[2 * i + 1] * u2[2 * i + 1]);
;                     }
; #pragma unroll
;                     for (int i = 0; i < 8; ++i) { ss += cv[i] * cv[i]; u2[i] = u1[i]; u1[i] = uu[i]; }
;                     ss = wave_sum(ss);
;                     const float rc = rsqrtf(ss * (1.0f / 512.0f) + EPS);
;                     u32x4 oc;
; #pragma unroll
	v_lshlrev_b32_e32 v204, 16, v30
	v_and_b32_e32 v205, 0xffff0000, v30
	v_lshlrev_b32_e32 v206, 16, v31
	v_and_b32_e32 v207, 0xffff0000, v31
	v_lshlrev_b32_e32 v208, 16, v32
	v_and_b32_e32 v209, 0xffff0000, v32
	v_lshlrev_b32_e32 v210, 16, v33
	v_and_b32_e32 v211, 0xffff0000, v33
	v_mul_f32_e32 v140, v164, v204
	v_mul_f32_e32 v141, v165, v205
	v_mul_f32_e32 v142, v166, v206
	v_mul_f32_e32 v143, v167, v207
	v_mul_f32_e32 v144, v168, v208
	v_mul_f32_e32 v145, v169, v209
	v_mul_f32_e32 v146, v170, v210
	v_mul_f32_e32 v147, v171, v211
	v_fmac_f32_e32 v140, v172, v196
	v_fmac_f32_e32 v141, v173, v197
	v_fmac_f32_e32 v142, v174, v198
	v_fmac_f32_e32 v143, v175, v199
	v_fmac_f32_e32 v144, v176, v200
	v_fmac_f32_e32 v145, v177, v201
	v_fmac_f32_e32 v146, v178, v202
	v_fmac_f32_e32 v147, v179, v203
	v_fmac_f32_e32 v140, v180, v188
	v_fmac_f32_e32 v141, v181, v189
	v_fmac_f32_e32 v142, v182, v190
	v_fmac_f32_e32 v143, v183, v191
	v_fmac_f32_e32 v144, v184, v192
	v_fmac_f32_e32 v145, v185, v193
	v_fmac_f32_e32 v146, v186, v194
	v_fmac_f32_e32 v147, v187, v195
	v_lshlrev_b32_e32 v150, 16, v14
	v_and_b32_e32 v151, 0xffff0000, v14
	v_mul_f32_e32 v140, v150, v140
	v_mul_f32_e32 v141, v151, v141
	v_lshlrev_b32_e32 v150, 16, v15
	v_and_b32_e32 v151, 0xffff0000, v15
	v_mul_f32_e32 v142, v150, v142
	v_mul_f32_e32 v143, v151, v143
	v_lshlrev_b32_e32 v150, 16, v16
	v_and_b32_e32 v151, 0xffff0000, v16
	v_mul_f32_e32 v144, v150, v144
	v_mul_f32_e32 v145, v151, v145
	v_lshlrev_b32_e32 v150, 16, v17
	v_and_b32_e32 v151, 0xffff0000, v17
	v_mul_f32_e32 v146, v150, v146
	v_mul_f32_e32 v147, v151, v147
	v_mul_f32_e32 v148, v140, v140
	v_fmac_f32_e32 v148, v141, v141
	v_fmac_f32_e32 v148, v142, v142
	v_fmac_f32_e32 v148, v143, v143
	v_fmac_f32_e32 v148, v144, v144
	v_fmac_f32_e32 v148, v145, v145
	v_fmac_f32_e32 v148, v146, v146
	v_fmac_f32_e32 v148, v147, v147
	v_mad_i64_i32 v[152:153], vcc, s41, v221, v[58:59]
	s_add_u32 s41, s41, 1
	global_load_dwordx4 v[14:17], v[152:153], off offset:1536
	global_load_dwordx4 v[30:33], v[152:153], off offset:2560
	s_nop 1
	v_add_f32_dpp v148, v148, v148 quad_perm:[1,0,3,2] row_mask:0xf bank_mask:0xf
	s_nop 1
	v_add_f32_dpp v148, v148, v148 quad_perm:[2,3,0,1] row_mask:0xf bank_mask:0xf
	s_nop 1
	v_add_f32_dpp v148, v148, v148 row_half_mirror row_mask:0xf bank_mask:0xf
	s_nop 1
	v_add_f32_dpp v148, v148, v148 row_mirror row_mask:0xf bank_mask:0xf
	s_nop 1
	v_add_f32_dpp v148, v148, v148 row_bcast:15 row_mask:0xa bank_mask:0xf
	s_nop 1
	v_add_f32_dpp v148, v148, v148 row_bcast:31 row_mask:0xc bank_mask:0xf
	s_nop 0
	v_readlane_b32 s0, v148, 63
	s_nop 1
	v_mov_b32_e32 v148, s0
	v_fmamk_f32 v148, v148, 0x3b000000, v162
	v_mul_f32_e32 v150, 0x4b800000, v148
	v_cmp_gt_f32_e32 vcc, s31, v148
	s_nop 1
	v_cndmask_b32_e32 v148, v148, v150, vcc
	v_rsq_f32_e32 v148, v148
	s_nop 0
	v_mul_f32_e32 v150, 0x45800000, v148
	v_cndmask_b32_e32 v149, v148, v150, vcc
	v_mul_f32_e32 v140, v149, v140
	v_mul_f32_e32 v141, v149, v141
	v_mul_f32_e32 v142, v149, v142
	v_mul_f32_e32 v143, v149, v143
	v_mul_f32_e32 v144, v149, v144
	v_mul_f32_e32 v145, v149, v145
	v_mul_f32_e32 v146, v149, v146
	v_mul_f32_e32 v147, v149, v147
	v_cvt_pk_bf16_f32 v140, v140, v141
	v_cvt_pk_bf16_f32 v141, v142, v143
	v_cvt_pk_bf16_f32 v142, v144, v145
	v_cvt_pk_bf16_f32 v143, v146, v147
	global_store_dwordx4 v[156:157], v[140:143], off offset:2048 sc1
	v_lshl_add_u64 v[156:157], v[156:157], 0, s[20:21]
	s_waitcnt vmcnt(10)
	v_lshlrev_b32_e32 v188, 16, v18
	v_and_b32_e32 v189, 0xffff0000, v18
	v_lshlrev_b32_e32 v190, 16, v19
	v_and_b32_e32 v191, 0xffff0000, v19
	v_lshlrev_b32_e32 v192, 16, v20
	v_and_b32_e32 v193, 0xffff0000, v20
	v_lshlrev_b32_e32 v194, 16, v21
	v_and_b32_e32 v195, 0xffff0000, v21
	v_mul_f32_e32 v140, v164, v188
	v_mul_f32_e32 v141, v165, v189
	v_mul_f32_e32 v142, v166, v190
	v_mul_f32_e32 v143, v167, v191
	v_mul_f32_e32 v144, v168, v192
	v_mul_f32_e32 v145, v169, v193
	v_mul_f32_e32 v146, v170, v194
	v_mul_f32_e32 v147, v171, v195
	v_fmac_f32_e32 v140, v172, v204
	v_fmac_f32_e32 v141, v173, v205
	v_fmac_f32_e32 v142, v174, v206
	v_fmac_f32_e32 v143, v175, v207
	v_fmac_f32_e32 v144, v176, v208
	v_fmac_f32_e32 v145, v177, v209
	v_fmac_f32_e32 v146, v178, v210
	v_fmac_f32_e32 v147, v179, v211
	v_fmac_f32_e32 v140, v180, v196
	v_fmac_f32_e32 v141, v181, v197
	v_fmac_f32_e32 v142, v182, v198
	v_fmac_f32_e32 v143, v183, v199
	v_fmac_f32_e32 v144, v184, v200
	v_fmac_f32_e32 v145, v185, v201
	v_fmac_f32_e32 v146, v186, v202
	v_fmac_f32_e32 v147, v187, v203
	v_lshlrev_b32_e32 v150, 16, v2
	v_and_b32_e32 v151, 0xffff0000, v2
	v_mul_f32_e32 v140, v150, v140
	v_mul_f32_e32 v141, v151, v141
	v_lshlrev_b32_e32 v150, 16, v3
	v_and_b32_e32 v151, 0xffff0000, v3
	v_mul_f32_e32 v142, v150, v142
	v_mul_f32_e32 v143, v151, v143
	v_lshlrev_b32_e32 v150, 16, v4
	v_and_b32_e32 v151, 0xffff0000, v4
	v_mul_f32_e32 v144, v150, v144
	v_mul_f32_e32 v145, v151, v145
	v_lshlrev_b32_e32 v150, 16, v5
	v_and_b32_e32 v151, 0xffff0000, v5
	v_mul_f32_e32 v146, v150, v146
	v_mul_f32_e32 v147, v151, v147
	v_mul_f32_e32 v148, v140, v140
	v_fmac_f32_e32 v148, v141, v141
	v_fmac_f32_e32 v148, v142, v142
	v_fmac_f32_e32 v148, v143, v143
	v_fmac_f32_e32 v148, v144, v144
	v_fmac_f32_e32 v148, v145, v145
	v_fmac_f32_e32 v148, v146, v146
	v_fmac_f32_e32 v148, v147, v147
	s_nop 1
	v_add_f32_dpp v148, v148, v148 quad_perm:[1,0,3,2] row_mask:0xf bank_mask:0xf
	s_nop 1
	v_add_f32_dpp v148, v148, v148 quad_perm:[2,3,0,1] row_mask:0xf bank_mask:0xf
	s_nop 1
	v_add_f32_dpp v148, v148, v148 row_half_mirror row_mask:0xf bank_mask:0xf
	s_nop 1
	v_add_f32_dpp v148, v148, v148 row_mirror row_mask:0xf bank_mask:0xf
	s_nop 1
	v_add_f32_dpp v148, v148, v148 row_bcast:15 row_mask:0xa bank_mask:0xf
	s_nop 1
	v_add_f32_dpp v148, v148, v148 row_bcast:31 row_mask:0xc bank_mask:0xf
	s_nop 0
	v_readlane_b32 s0, v148, 63
	s_nop 1
	v_mov_b32_e32 v148, s0
	v_fmamk_f32 v148, v148, 0x3b000000, v162
	v_mul_f32_e32 v150, 0x4b800000, v148
	v_cmp_gt_f32_e32 vcc, s31, v148
	s_nop 1
	v_cndmask_b32_e32 v148, v148, v150, vcc
	v_rsq_f32_e32 v148, v148
	s_nop 0
	v_mul_f32_e32 v150, 0x45800000, v148
	v_cndmask_b32_e32 v149, v148, v150, vcc
	v_mul_f32_e32 v140, v149, v140
	v_mul_f32_e32 v141, v149, v141
	v_mul_f32_e32 v142, v149, v142
	v_mul_f32_e32 v143, v149, v143
	v_mul_f32_e32 v144, v149, v144
	v_mul_f32_e32 v145, v149, v145
	v_mul_f32_e32 v146, v149, v146
	v_mul_f32_e32 v147, v149, v147
	v_cvt_pk_bf16_f32 v140, v140, v141
	v_cvt_pk_bf16_f32 v141, v142, v143
	v_cvt_pk_bf16_f32 v142, v144, v145
	v_cvt_pk_bf16_f32 v143, v146, v147
	global_store_dwordx4 v[156:157], v[140:143], off sc1
	s_waitcnt vmcnt(8)
; __device__ __forceinline__ float bf_lo(unsigned w) { return __uint_as_float(w << 16); }
; __global__ void __launch_bounds__(512, 2) trunk_fwd(Args args) {
;     ...
;             for (int ch = gw; ch < M / 16; ch += NGW) {
;                 const int r0 = ch * 16, t0 = r0 & (SEQ - 1), c0 = lane * 8;
;                 float w0[8], w1[8], w2[8], u1[8], u2[8];
; #pragma unroll
;                 for (int i = 0; i < 8; ++i) { w0[i] = cw[c0 + i]; w1[i] = cw[512 + c0 + i]; w2[i] = cw[1024 + c0 + i]; u1[i] = 0.f; u2[i] = 0.f; }
;                 if (t0 != 0) {
;                     const u32x4 c1 = *(const u32x4*)(Z + (size_t)(r0 - 1) * INP + 1280 + c0), c2 = *(const u32x4*)(Z + (size_t)(r0 - 2) * INP + 1280 + c0);
; #pragma unroll
;                     for (int i = 0; i < 4; ++i) { u1[2 * i] = bf_lo(c1[i]); u1[2 * i + 1] = bf_hi(c1[i]); u2[2 * i] = bf_lo(c2[i]); u2[2 * i + 1] = bf_hi(c2[i]); }
;                 }
;                 u32x4 gb_n = *(const u32x4*)(Z + (size_t)r0 * INP + 768 + c0), gu_n = *(const u32x4*)(Z + (size_t)r0 * INP + 1280 + c0);
;                 f32x4 pv_n = *(const f32x4*)(pl + (size_t)r0 * PLE + lane * 4);
; #pragma nounroll
;                 for (int rr = 0; rr < 16; ++rr) {
;                     const int r = r0 + rr;
;                     const u32x4 gb = gb_n, gu = gu_n; const f32x4 pv4 = pv_n;
;                     if (rr < 15) { gb_n = *(const u32x4*)(Z + (size_t)(r + 1) * INP + 768 + c0); gu_n = *(const u32x4*)(Z + (size_t)(r + 1) * INP + 1280 + c0);
;                                    pv_n = *(const f32x4*)(pl + (size_t)(r + 1) * PLE + lane * 4); }
;                     float cv[8], uu[8]; float ss = 0.f;
; #pragma unroll
;                     for (int i = 0; i < 4; ++i) {
;                         uu[2 * i] = bf_lo(gu[i]); uu[2 * i + 1] = bf_hi(gu[i]);
;                         cv[2 * i] = bf_lo(gb[i]) * (w0[2 * i] * uu[2 * i] + w1[2 * i] * u1[2 * i] + w2[2 * i] * u2[2 * i]);
;                         cv[2 * i + 1] = bf_hi(gb[i]) * (w0[2 * i + 1] * uu[2 * i + 1] + w1[2 * i + 1] * u1[2 * i + 1] + w2[2 * i + 1] * u2[2 * i + 1]);
;                     }
; #pragma unroll
;                     for (int i = 0; i < 8; ++i) { ss += cv[i] * cv[i]; u2[i] = u1[i]; u1[i] = uu[i]; }
;                     ss = wave_sum(ss);
;                     const float rc = rsqrtf(ss * (1.0f / 512.0f) + EPS);
;                     u32x4 oc;
; #pragma unroll
	v_lshlrev_b32_e32 v196, 16, v22
	v_and_b32_e32 v197, 0xffff0000, v22
	v_lshlrev_b32_e32 v198, 16, v23
	v_and_b32_e32 v199, 0xffff0000, v23
	v_lshlrev_b32_e32 v200, 16, v24
	v_and_b32_e32 v201, 0xffff0000, v24
	v_lshlrev_b32_e32 v202, 16, v25
	v_and_b32_e32 v203, 0xffff0000, v25
	v_mul_f32_e32 v140, v164, v196
	v_mul_f32_e32 v141, v165, v197
	v_mul_f32_e32 v142, v166, v198
	v_mul_f32_e32 v143, v167, v199
	v_mul_f32_e32 v144, v168, v200
	v_mul_f32_e32 v145, v169, v201
	v_mul_f32_e32 v146, v170, v202
	v_mul_f32_e32 v147, v171, v203
	v_fmac_f32_e32 v140, v172, v188
	v_fmac_f32_e32 v141, v173, v189
	v_fmac_f32_e32 v142, v174, v190
	v_fmac_f32_e32 v143, v175, v191
	v_fmac_f32_e32 v144, v176, v192
	v_fmac_f32_e32 v145, v177, v193
	v_fmac_f32_e32 v146, v178, v194
	v_fmac_f32_e32 v147, v179, v195
	v_fmac_f32_e32 v140, v180, v204
	v_fmac_f32_e32 v141, v181, v205
	v_fmac_f32_e32 v142, v182, v206
	v_fmac_f32_e32 v143, v183, v207
	v_fmac_f32_e32 v144, v184, v208
	v_fmac_f32_e32 v145, v185, v209
	v_fmac_f32_e32 v146, v186, v210
	v_fmac_f32_e32 v147, v187, v211
	v_lshlrev_b32_e32 v150, 16, v6
	v_and_b32_e32 v151, 0xffff0000, v6
	v_mul_f32_e32 v140, v150, v140
	v_mul_f32_e32 v141, v151, v141
	v_lshlrev_b32_e32 v150, 16, v7
	v_and_b32_e32 v151, 0xffff0000, v7
	v_mul_f32_e32 v142, v150, v142
	v_mul_f32_e32 v143, v151, v143
	v_lshlrev_b32_e32 v150, 16, v8
	v_and_b32_e32 v151, 0xffff0000, v8
	v_mul_f32_e32 v144, v150, v144
	v_mul_f32_e32 v145, v151, v145
	v_lshlrev_b32_e32 v150, 16, v9
	v_and_b32_e32 v151, 0xffff0000, v9
	v_mul_f32_e32 v146, v150, v146
	v_mul_f32_e32 v147, v151, v147
	v_mul_f32_e32 v148, v140, v140
	v_fmac_f32_e32 v148, v141, v141
	v_fmac_f32_e32 v148, v142, v142
	v_fmac_f32_e32 v148, v143, v143
	v_fmac_f32_e32 v148, v144, v144
	v_fmac_f32_e32 v148, v145, v145
	v_fmac_f32_e32 v148, v146, v146
	v_fmac_f32_e32 v148, v147, v147
	s_nop 1
	v_add_f32_dpp v148, v148, v148 quad_perm:[1,0,3,2] row_mask:0xf bank_mask:0xf
	s_nop 1
	v_add_f32_dpp v148, v148, v148 quad_perm:[2,3,0,1] row_mask:0xf bank_mask:0xf
	s_nop 1
	v_add_f32_dpp v148, v148, v148 row_half_mirror row_mask:0xf bank_mask:0xf
	s_nop 1
	v_add_f32_dpp v148, v148, v148 row_mirror row_mask:0xf bank_mask:0xf
	s_nop 1
	v_add_f32_dpp v148, v148, v148 row_bcast:15 row_mask:0xa bank_mask:0xf
	s_nop 1
	v_add_f32_dpp v148, v148, v148 row_bcast:31 row_mask:0xc bank_mask:0xf
	s_nop 0
	v_readlane_b32 s0, v148, 63
	s_nop 1
	v_mov_b32_e32 v148, s0
	v_fmamk_f32 v148, v148, 0x3b000000, v162
	v_mul_f32_e32 v150, 0x4b800000, v148
	v_cmp_gt_f32_e32 vcc, s31, v148
	s_nop 1
	v_cndmask_b32_e32 v148, v148, v150, vcc
	v_rsq_f32_e32 v148, v148
	s_nop 0
	v_mul_f32_e32 v150, 0x45800000, v148
	v_cndmask_b32_e32 v149, v148, v150, vcc
	v_mul_f32_e32 v140, v149, v140
	v_mul_f32_e32 v141, v149, v141
	v_mul_f32_e32 v142, v149, v142
	v_mul_f32_e32 v143, v149, v143
	v_mul_f32_e32 v144, v149, v144
	v_mul_f32_e32 v145, v149, v145
	v_mul_f32_e32 v146, v149, v146
	v_mul_f32_e32 v147, v149, v147
	v_cvt_pk_bf16_f32 v140, v140, v141
	v_cvt_pk_bf16_f32 v141, v142, v143
	v_cvt_pk_bf16_f32 v142, v144, v145
	v_cvt_pk_bf16_f32 v143, v146, v147
	global_store_dwordx4 v[156:157], v[140:143], off offset:2048 sc1
	v_lshl_add_u64 v[156:157], v[156:157], 0, s[20:21]
	s_waitcnt vmcnt(6)
	v_lshlrev_b32_e32 v204, 16, v26
	v_and_b32_e32 v205, 0xffff0000, v26
	v_lshlrev_b32_e32 v206, 16, v27
	v_and_b32_e32 v207, 0xffff0000, v27
	v_lshlrev_b32_e32 v208, 16, v28
	v_and_b32_e32 v209, 0xffff0000, v28
	v_lshlrev_b32_e32 v210, 16, v29
	v_and_b32_e32 v211, 0xffff0000, v29
	v_mul_f32_e32 v140, v164, v204
	v_mul_f32_e32 v141, v165, v205
	v_mul_f32_e32 v142, v166, v206
	v_mul_f32_e32 v143, v167, v207
	v_mul_f32_e32 v144, v168, v208
	v_mul_f32_e32 v145, v169, v209
	v_mul_f32_e32 v146, v170, v210
	v_mul_f32_e32 v147, v171, v211
	v_fmac_f32_e32 v140, v172, v196
	v_fmac_f32_e32 v141, v173, v197
	v_fmac_f32_e32 v142, v174, v198
	v_fmac_f32_e32 v143, v175, v199
	v_fmac_f32_e32 v144, v176, v200
	v_fmac_f32_e32 v145, v177, v201
	v_fmac_f32_e32 v146, v178, v202
	v_fmac_f32_e32 v147, v179, v203
	v_fmac_f32_e32 v140, v180, v188
	v_fmac_f32_e32 v141, v181, v189
	v_fmac_f32_e32 v142, v182, v190
	v_fmac_f32_e32 v143, v183, v191
	v_fmac_f32_e32 v144, v184, v192
	v_fmac_f32_e32 v145, v185, v193
	v_fmac_f32_e32 v146, v186, v194
	v_fmac_f32_e32 v147, v187, v195
	v_lshlrev_b32_e32 v150, 16, v10
	v_and_b32_e32 v151, 0xffff0000, v10
	v_mul_f32_e32 v140, v150, v140
	v_mul_f32_e32 v141, v151, v141
	v_lshlrev_b32_e32 v150, 16, v11
	v_and_b32_e32 v151, 0xffff0000, v11
	v_mul_f32_e32 v142, v150, v142
	v_mul_f32_e32 v143, v151, v143
	v_lshlrev_b32_e32 v150, 16, v12
	v_and_b32_e32 v151, 0xffff0000, v12
	v_mul_f32_e32 v144, v150, v144
	v_mul_f32_e32 v145, v151, v145
	v_lshlrev_b32_e32 v150, 16, v13
	v_and_b32_e32 v151, 0xffff0000, v13
	v_mul_f32_e32 v146, v150, v146
	v_mul_f32_e32 v147, v151, v147
	v_mul_f32_e32 v148, v140, v140
	v_fmac_f32_e32 v148, v141, v141
	v_fmac_f32_e32 v148, v142, v142
	v_fmac_f32_e32 v148, v143, v143
	v_fmac_f32_e32 v148, v144, v144
	v_fmac_f32_e32 v148, v145, v145
	v_fmac_f32_e32 v148, v146, v146
	v_fmac_f32_e32 v148, v147, v147
	s_nop 1
	v_add_f32_dpp v148, v148, v148 quad_perm:[1,0,3,2] row_mask:0xf bank_mask:0xf
	s_nop 1
	v_add_f32_dpp v148, v148, v148 quad_perm:[2,3,0,1] row_mask:0xf bank_mask:0xf
	s_nop 1
	v_add_f32_dpp v148, v148, v148 row_half_mirror row_mask:0xf bank_mask:0xf
	s_nop 1
	v_add_f32_dpp v148, v148, v148 row_mirror row_mask:0xf bank_mask:0xf
	s_nop 1
	v_add_f32_dpp v148, v148, v148 row_bcast:15 row_mask:0xa bank_mask:0xf
	s_nop 1
	v_add_f32_dpp v148, v148, v148 row_bcast:31 row_mask:0xc bank_mask:0xf
	s_nop 0
	v_readlane_b32 s0, v148, 63
	s_nop 1
	v_mov_b32_e32 v148, s0
	v_fmamk_f32 v148, v148, 0x3b000000, v162
	v_mul_f32_e32 v150, 0x4b800000, v148
	v_cmp_gt_f32_e32 vcc, s31, v148
	s_nop 1
	v_cndmask_b32_e32 v148, v148, v150, vcc
	v_rsq_f32_e32 v148, v148
	s_nop 0
	v_mul_f32_e32 v150, 0x45800000, v148
	v_cndmask_b32_e32 v149, v148, v150, vcc
	v_mul_f32_e32 v140, v149, v140
	v_mul_f32_e32 v141, v149, v141
	v_mul_f32_e32 v142, v149, v142
	v_mul_f32_e32 v143, v149, v143
	v_mul_f32_e32 v144, v149, v144
	v_mul_f32_e32 v145, v149, v145
	v_mul_f32_e32 v146, v149, v146
	v_mul_f32_e32 v147, v149, v147
	v_cvt_pk_bf16_f32 v140, v140, v141
	v_cvt_pk_bf16_f32 v141, v142, v143
	v_cvt_pk_bf16_f32 v142, v144, v145
	v_cvt_pk_bf16_f32 v143, v146, v147
	global_store_dwordx4 v[156:157], v[140:143], off sc1
	s_waitcnt vmcnt(4)
; __device__ __forceinline__ float bf_lo(unsigned w) { return __uint_as_float(w << 16); }
; __global__ void __launch_bounds__(512, 2) trunk_fwd(Args args) {
;     ...
;             for (int ch = gw; ch < M / 16; ch += NGW) {
;                 const int r0 = ch * 16, t0 = r0 & (SEQ - 1), c0 = lane * 8;
;                 float w0[8], w1[8], w2[8], u1[8], u2[8];
; #pragma unroll
;                 for (int i = 0; i < 8; ++i) { w0[i] = cw[c0 + i]; w1[i] = cw[512 + c0 + i]; w2[i] = cw[1024 + c0 + i]; u1[i] = 0.f; u2[i] = 0.f; }
;                 if (t0 != 0) {
;                     const u32x4 c1 = *(const u32x4*)(Z + (size_t)(r0 - 1) * INP + 1280 + c0), c2 = *(const u32x4*)(Z + (size_t)(r0 - 2) * INP + 1280 + c0);
; #pragma unroll
;                     for (int i = 0; i < 4; ++i) { u1[2 * i] = bf_lo(c1[i]); u1[2 * i + 1] = bf_hi(c1[i]); u2[2 * i] = bf_lo(c2[i]); u2[2 * i + 1] = bf_hi(c2[i]); }
;                 }
;                 u32x4 gb_n = *(const u32x4*)(Z + (size_t)r0 * INP + 768 + c0), gu_n = *(const u32x4*)(Z + (size_t)r0 * INP + 1280 + c0);
;                 f32x4 pv_n = *(const f32x4*)(pl + (size_t)r0 * PLE + lane * 4);
; #pragma nounroll
;                 for (int rr = 0; rr < 16; ++rr) {
;                     const int r = r0 + rr;
;                     const u32x4 gb = gb_n, gu = gu_n; const f32x4 pv4 = pv_n;
;                     if (rr < 15) { gb_n = *(const u32x4*)(Z + (size_t)(r + 1) * INP + 768 + c0); gu_n = *(const u32x4*)(Z + (size_t)(r + 1) * INP + 1280 + c0);
;                                    pv_n = *(const f32x4*)(pl + (size_t)(r + 1) * PLE + lane * 4); }
;                     float cv[8], uu[8]; float ss = 0.f;
; #pragma unroll
;                     for (int i = 0; i < 4; ++i) {
;                         uu[2 * i] = bf_lo(gu[i]); uu[2 * i + 1] = bf_hi(gu[i]);
;                         cv[2 * i] = bf_lo(gb[i]) * (w0[2 * i] * uu[2 * i] + w1[2 * i] * u1[2 * i] + w2[2 * i] * u2[2 * i]);
;                         cv[2 * i + 1] = bf_hi(gb[i]) * (w0[2 * i + 1] * uu[2 * i + 1] + w1[2 * i + 1] * u1[2 * i + 1] + w2[2 * i + 1] * u2[2 * i + 1]);
;                     }
; #pragma unroll
;                     for (int i = 0; i < 8; ++i) { ss += cv[i] * cv[i]; u2[i] = u1[i]; u1[i] = uu[i]; }
;                     ss = wave_sum(ss);
;                     const float rc = rsqrtf(ss * (1.0f / 512.0f) + EPS);
;                     u32x4 oc;
; #pragma unroll
	v_lshlrev_b32_e32 v188, 16, v30
	v_and_b32_e32 v189, 0xffff0000, v30
	v_lshlrev_b32_e32 v190, 16, v31
	v_and_b32_e32 v191, 0xffff0000, v31
	v_lshlrev_b32_e32 v192, 16, v32
	v_and_b32_e32 v193, 0xffff0000, v32
	v_lshlrev_b32_e32 v194, 16, v33
	v_and_b32_e32 v195, 0xffff0000, v33
	v_mul_f32_e32 v140, v164, v188
	v_mul_f32_e32 v141, v165, v189
	v_mul_f32_e32 v142, v166, v190
	v_mul_f32_e32 v143, v167, v191
	v_mul_f32_e32 v144, v168, v192
	v_mul_f32_e32 v145, v169, v193
	v_mul_f32_e32 v146, v170, v194
	v_mul_f32_e32 v147, v171, v195
	v_fmac_f32_e32 v140, v172, v204
	v_fmac_f32_e32 v141, v173, v205
	v_fmac_f32_e32 v142, v174, v206
	v_fmac_f32_e32 v143, v175, v207
	v_fmac_f32_e32 v144, v176, v208
	v_fmac_f32_e32 v145, v177, v209
	v_fmac_f32_e32 v146, v178, v210
	v_fmac_f32_e32 v147, v179, v211
	v_fmac_f32_e32 v140, v180, v196
	v_fmac_f32_e32 v141, v181, v197
	v_fmac_f32_e32 v142, v182, v198
	v_fmac_f32_e32 v143, v183, v199
	v_fmac_f32_e32 v144, v184, v200
	v_fmac_f32_e32 v145, v185, v201
	v_fmac_f32_e32 v146, v186, v202
	v_fmac_f32_e32 v147, v187, v203
	v_lshlrev_b32_e32 v150, 16, v14
	v_and_b32_e32 v151, 0xffff0000, v14
	v_mul_f32_e32 v140, v150, v140
	v_mul_f32_e32 v141, v151, v141
	v_lshlrev_b32_e32 v150, 16, v15
	v_and_b32_e32 v151, 0xffff0000, v15
	v_mul_f32_e32 v142, v150, v142
	v_mul_f32_e32 v143, v151, v143
	v_lshlrev_b32_e32 v150, 16, v16
	v_and_b32_e32 v151, 0xffff0000, v16
	v_mul_f32_e32 v144, v150, v144
	v_mul_f32_e32 v145, v151, v145
	v_lshlrev_b32_e32 v150, 16, v17
	v_and_b32_e32 v151, 0xffff0000, v17
	v_mul_f32_e32 v146, v150, v146
	v_mul_f32_e32 v147, v151, v147
	v_mul_f32_e32 v148, v140, v140
	v_fmac_f32_e32 v148, v141, v141
	v_fmac_f32_e32 v148, v142, v142
	v_fmac_f32_e32 v148, v143, v143
	v_fmac_f32_e32 v148, v144, v144
	v_fmac_f32_e32 v148, v145, v145
	v_fmac_f32_e32 v148, v146, v146
	v_fmac_f32_e32 v148, v147, v147
	s_nop 1
	v_add_f32_dpp v148, v148, v148 quad_perm:[1,0,3,2] row_mask:0xf bank_mask:0xf
	s_nop 1
	v_add_f32_dpp v148, v148, v148 quad_perm:[2,3,0,1] row_mask:0xf bank_mask:0xf
	s_nop 1
	v_add_f32_dpp v148, v148, v148 row_half_mirror row_mask:0xf bank_mask:0xf
	s_nop 1
	v_add_f32_dpp v148, v148, v148 row_mirror row_mask:0xf bank_mask:0xf
	s_nop 1
	v_add_f32_dpp v148, v148, v148 row_bcast:15 row_mask:0xa bank_mask:0xf
	s_nop 1
	v_add_f32_dpp v148, v148, v148 row_bcast:31 row_mask:0xc bank_mask:0xf
	s_nop 0
	v_readlane_b32 s0, v148, 63
	s_nop 1
	v_mov_b32_e32 v148, s0
	v_fmamk_f32 v148, v148, 0x3b000000, v162
	v_mul_f32_e32 v150, 0x4b800000, v148
	v_cmp_gt_f32_e32 vcc, s31, v148
	s_nop 1
	v_cndmask_b32_e32 v148, v148, v150, vcc
	v_rsq_f32_e32 v148, v148
	s_nop 0
	v_mul_f32_e32 v150, 0x45800000, v148
	v_cndmask_b32_e32 v149, v148, v150, vcc
	v_mul_f32_e32 v140, v149, v140
	v_mul_f32_e32 v141, v149, v141
	v_mul_f32_e32 v142, v149, v142
	v_mul_f32_e32 v143, v149, v143
	v_mul_f32_e32 v144, v149, v144
	v_mul_f32_e32 v145, v149, v145
	v_mul_f32_e32 v146, v149, v146
	v_mul_f32_e32 v147, v149, v147
	v_cvt_pk_bf16_f32 v140, v140, v141
	v_cvt_pk_bf16_f32 v141, v142, v143
	v_cvt_pk_bf16_f32 v142, v144, v145
	v_cvt_pk_bf16_f32 v143, v146, v147
	global_store_dwordx4 v[156:157], v[140:143], off offset:2048 sc1
	v_lshl_add_u64 v[156:157], v[156:157], 0, s[20:21]
	s_branch .LBB0_1053

; #define LAS __attribute__((address_space(3)))
; __device__ __forceinline__ unsigned cvt_pk_bf16(float lo, float hi) { unsigned r; asm volatile("v_cvt_pk_bf16_f32 %0, %1, %2" : "=v"(r) : "v"(lo), "v"(hi)); return r; }
; __device__ __forceinline__ void wconv_item(const float* W, int K, int Norig, int Nphys, bf16_t* WT, const float* gA, const float* gB, int split, int mapid, LAS float* scr, int item, int lane) {
;     ...
;     for (int i = 0; i < 32; ++i) { const int kk = 2 * i + (lane >> 5), k = k0 + kk;
;         float v = wv[i];
;         if (gA) v *= (k < split ? gA[k] : gB[k - split]);
;         scr[kk * 33 + (lane & 31)] = v; }
;     asm volatile("s_waitcnt lgkmcnt(0)" ::: "memory");
;     const int c = lane & 7;
; #pragma unroll
;     for (int j = 0; j < 4; ++j) { const int n = (lane >> 3) + 8 * j; const LAS float* s = scr + (8 * c) * 33 + n;
;         u32x4 o; o.x = cvt_pk_bf16(s[0 * 33], s[1 * 33]); o.y = cvt_pk_bf16(s[2 * 33], s[3 * 33]); o.z = cvt_pk_bf16(s[4 * 33], s[5 * 33]); o.w = cvt_pk_bf16(s[6 * 33], s[7 * 33]);
;         *(u32x4*)(WT + (size_t)(n0 + n) * K + k0 + 8 * c) = o; }
;     asm volatile("s_waitcnt lgkmcnt(0)" ::: "memory");
.LBB0_1064:
	v_add_u32_e32 v0, 0x400, v28
	ds_write2_b32 v0, v24, v25 offset0:8 offset1:74
	ds_write2_b32 v0, v26, v27 offset0:140 offset1:206
	s_waitcnt lgkmcnt(0)
	ds_read2_b32 v[20:21], v46 offset1:33
	s_waitcnt lgkmcnt(0)
	v_cvt_pk_bf16_f32 v20, v20, v21
	ds_read2_b32 v[22:23], v46 offset0:66 offset1:99
	s_waitcnt lgkmcnt(0)
	v_cvt_pk_bf16_f32 v21, v22, v23
	ds_read2_b32 v[22:23], v46 offset0:132 offset1:165
	s_waitcnt lgkmcnt(0)
	v_cvt_pk_bf16_f32 v22, v22, v23
	ds_read2_b32 v[26:27], v46 offset0:198 offset1:231
	s_waitcnt lgkmcnt(0)
	v_cvt_pk_bf16_f32 v23, v26, v27
	v_add_u32_e32 v26, s48, v45
	v_ashrrev_i32_e32 v27, 31, v26
	v_lshl_add_u64 v[24:25], s[64:65], 1, v[18:19]
	v_lshlrev_b64 v[28:29], 11, v[26:27]
	v_lshl_add_u64 v[28:29], v[24:25], 0, v[28:29]
	global_store_dwordx4 v[28:29], v[20:23], off sc1
	ds_read2_b32 v[20:21], v46 offset0:8 offset1:41
	s_waitcnt lgkmcnt(0)
	v_cvt_pk_bf16_f32 v20, v20, v21
	ds_read2_b32 v[22:23], v46 offset0:74 offset1:107
	s_waitcnt lgkmcnt(0)
	v_cvt_pk_bf16_f32 v21, v22, v23
	ds_read2_b32 v[22:23], v46 offset0:140 offset1:173
	s_waitcnt lgkmcnt(0)
	v_cvt_pk_bf16_f32 v22, v22, v23
	ds_read2_b32 v[28:29], v46 offset0:206 offset1:239
	s_waitcnt lgkmcnt(0)
	v_cvt_pk_bf16_f32 v23, v28, v29
	v_add_u32_e32 v28, 8, v26
	v_ashrrev_i32_e32 v29, 31, v28
	v_lshlrev_b64 v[28:29], 11, v[28:29]
	v_lshl_add_u64 v[28:29], v[24:25], 0, v[28:29]
	global_store_dwordx4 v[28:29], v[20:23], off sc1
	ds_read2_b32 v[20:21], v46 offset0:16 offset1:49
	s_waitcnt lgkmcnt(0)
	v_cvt_pk_bf16_f32 v20, v20, v21
	ds_read2_b32 v[22:23], v46 offset0:82 offset1:115
	s_waitcnt lgkmcnt(0)
	v_cvt_pk_bf16_f32 v21, v22, v23
	ds_read2_b32 v[22:23], v46 offset0:148 offset1:181
	s_waitcnt lgkmcnt(0)
	v_cvt_pk_bf16_f32 v22, v22, v23
	ds_read2_b32 v[28:29], v46 offset0:214 offset1:247
	s_waitcnt lgkmcnt(0)
	v_cvt_pk_bf16_f32 v23, v28, v29
	v_add_u32_e32 v28, 16, v26
	v_ashrrev_i32_e32 v29, 31, v28
	v_lshlrev_b64 v[28:29], 11, v[28:29]
	v_lshl_add_u64 v[28:29], v[24:25], 0, v[28:29]
	v_add_u32_e32 v26, 24, v26
	global_store_dwordx4 v[28:29], v[20:23], off sc1
	ds_read2_b32 v[20:21], v46 offset0:24 offset1:57
	v_ashrrev_i32_e32 v27, 31, v26
	s_waitcnt lgkmcnt(0)
	v_cvt_pk_bf16_f32 v20, v20, v21
	ds_read2_b32 v[22:23], v46 offset0:90 offset1:123
	v_lshlrev_b64 v[26:27], 11, v[26:27]
	s_waitcnt lgkmcnt(0)
	v_cvt_pk_bf16_f32 v21, v22, v23
	ds_read2_b32 v[22:23], v46 offset0:156 offset1:189
	v_lshl_add_u64 v[24:25], v[24:25], 0, v[26:27]
	s_waitcnt lgkmcnt(0)
	v_cvt_pk_bf16_f32 v22, v22, v23
	ds_read2_b32 v[28:29], v46 offset0:222 offset1:255
	s_waitcnt lgkmcnt(0)
	v_cvt_pk_bf16_f32 v23, v28, v29
	global_store_dwordx4 v[24:25], v[20:23], off sc1
	s_waitcnt lgkmcnt(0)

; __device__ __forceinline__ void wconv_item(const float* W, int K, int Norig, int Nphys, bf16_t* WT, const float* gA, const float* gB, int split, int mapid, LAS float* scr, int item, int lane) {
;     const int nblk = Nphys / 32, kb = item / nblk, nb = item % nblk, k0 = 64 * kb, n0 = 32 * nb;
;     const int norig = colmap(mapid, n0 + (lane & 31));
;     float wv[32];
; #pragma unroll
;     for (int i = 0; i < 32; ++i) { const int k = k0 + 2 * i + (lane >> 5); wv[i] = (norig >= 0) ? W[(size_t)k * Norig + norig] : 0.f; }
; template <class AP> __device__ __forceinline__ void convert_weights(AP a, int L, bf16_t* wb, LAS float* scr, int gw, int NGW, int lane) {
;     ...
;     for (int it = gw; it < NIT; it += NGW) {
;         int r = it;
;         if (r < I0) { wconv_item(w_in, 1024, INC, INP, wb + WO_IN, g_mix, g_mix, 1024, 0, scr, r, lane); continue; } r -= I0;
;         if (r < I1) { wconv_item(w_uq, QL, 768, 768, wb + WO_UQ, g_ql, g_ql, QL, 1, scr, r, lane); continue; } r -= I1;
;         if (r < I2) { wconv_item(w_ukv, KVL, 1024, 1024, wb + WO_UKV, g_kvl, g_kvl, KVL, 2, scr, r, lane); continue; } r -= I2;
;         if (r < I3) { wconv_item(w_o, 1024, 1024, 1024, wb + WO_O, g_oa, g_oc, 512, 3, scr, r, lane); continue; } r -= I3;
;         if (r < I4) { wconv_item(w_up, 1024, FF, FF, wb + WO_UP, g_mlp, g_mlp, 1024, 3, scr, r, lane); continue; } r -= I4;
;         if (r < I5) { wconv_item(w_dn, FF, 1024, 1024, wb + WO_DN, nullptr, nullptr, 0, 3, scr, r, lane); continue; } r -= I5;
;         if (r < I6) { wconv_item(w_g, 1024, 1024, 1024, wb + WO_G, g_ple, g_ple, 1024, 3, scr, r, lane); continue; } r -= I6;
;         wconv_item(w_ple, PLE, 1024, 1024, wb + WO_PLE, nullptr, nullptr, 0, 3, scr, r, lane);
.LBB0_1066:
	s_cmpk_gt_i32 s75, 0x47f
	s_mov_b64 s[38:39], -1
	s_cbranch_scc0 .LBB0_1160
	s_cmpk_gt_u32 s75, 0x50f
	s_cbranch_scc0 .LBB0_1141
	s_cmpk_gt_u32 s75, 0x58f
	s_cbranch_scc0 .LBB0_1122
	s_cmpk_gt_u32 s75, 0x78f
	s_cbranch_scc0 .LBB0_1107
	s_cmpk_gt_u32 s75, 0xf8f
	s_cbranch_scc0 .LBB0_1092
	s_cmpk_gt_u32 s75, 0x178f
	s_cbranch_scc0 .LBB0_1089
	s_cmpk_gt_u32 s75, 0x198f
	s_cbranch_scc0 .LBB0_1074
	s_add_i32 s4, s82, 0xfffcce00
	s_and_b32 s38, s4, 0x3e0
	s_and_b32 s39, s84, 0x1c0
	v_or_b32_e32 v0, s38, v42
	v_or_b32_e32 v22, s39, v2
	v_lshlrev_b32_e32 v0, 2, v0
	v_lshl_add_u64 v[20:21], s[66:67], 0, v[0:1]
	v_lshlrev_b32_e32 v0, 12, v22
	v_lshl_add_u64 v[20:21], v[20:21], 0, v[0:1]
	v_add_co_u32_e32 v22, vcc, 0x2000, v20
	global_load_dword v0, v[20:21], off
	s_nop 0
	v_addc_co_u32_e32 v23, vcc, 0, v21, vcc
	global_load_dword v24, v[22:23], off
	v_add_co_u32_e32 v22, vcc, 0x4000, v20
	s_mov_b32 s4, 0x10000
	s_nop 0
	v_addc_co_u32_e32 v23, vcc, 0, v21, vcc
	global_load_dword v25, v[22:23], off
	v_add_co_u32_e32 v22, vcc, 0x6000, v20
	s_lshl_b32 s48, s39, 1
	s_nop 0
	v_addc_co_u32_e32 v23, vcc, 0, v21, vcc
	global_load_dword v26, v[22:23], off
	v_add_co_u32_e32 v22, vcc, 0x8000, v20
	s_nop 1
	v_addc_co_u32_e32 v23, vcc, 0, v21, vcc
	global_load_dword v27, v[22:23], off
	v_add_co_u32_e32 v22, vcc, 0xa000, v20
	s_nop 1
	v_addc_co_u32_e32 v23, vcc, 0, v21, vcc
	global_load_dword v28, v[22:23], off
	v_add_co_u32_e32 v22, vcc, 0xc000, v20
	s_nop 1
	v_addc_co_u32_e32 v23, vcc, 0, v21, vcc
	global_load_dword v29, v[22:23], off
	v_add_co_u32_e32 v22, vcc, 0xe000, v20
	s_nop 1
	v_addc_co_u32_e32 v23, vcc, 0, v21, vcc
	global_load_dword v30, v[22:23], off
	v_add_co_u32_e32 v22, vcc, s4, v20
	s_mov_b32 s4, 0x12000
	s_nop 0
	v_addc_co_u32_e32 v23, vcc, 0, v21, vcc
	global_load_dword v31, v[22:23], off
	v_add_co_u32_e32 v22, vcc, s4, v20
	s_mov_b32 s4, 0x14000
	s_nop 0
	v_addc_co_u32_e32 v23, vcc, 0, v21, vcc
	global_load_dword v32, v[22:23], off
	v_add_co_u32_e32 v22, vcc, s4, v20
	s_mov_b32 s4, 0x16000
	s_nop 0
	v_addc_co_u32_e32 v23, vcc, 0, v21, vcc
	global_load_dword v33, v[22:23], off
	v_add_co_u32_e32 v22, vcc, s4, v20
	s_mov_b32 s4, 0x18000
	s_nop 0
	v_addc_co_u32_e32 v23, vcc, 0, v21, vcc
	global_load_dword v34, v[22:23], off
	v_add_co_u32_e32 v22, vcc, s4, v20
	s_mov_b32 s4, 0x1a000
	s_nop 0
	v_addc_co_u32_e32 v23, vcc, 0, v21, vcc
	global_load_dword v35, v[22:23], off
	v_add_co_u32_e32 v22, vcc, s4, v20
	s_mov_b32 s4, 0x1c000
	s_nop 0
	v_addc_co_u32_e32 v23, vcc, 0, v21, vcc
	global_load_dword v36, v[22:23], off
	v_add_co_u32_e32 v22, vcc, s4, v20
	s_mov_b32 s4, 0x1e000
	s_nop 0
	v_addc_co_u32_e32 v23, vcc, 0, v21, vcc
	global_load_dword v37, v[22:23], off
	v_add_co_u32_e32 v22, vcc, s4, v20
	s_mov_b32 s4, 0x20000
	s_nop 0
	v_addc_co_u32_e32 v23, vcc, 0, v21, vcc
	global_load_dword v38, v[22:23], off
	v_add_co_u32_e32 v22, vcc, s4, v20
	s_mov_b32 s4, 0x22000
	s_nop 0
	v_addc_co_u32_e32 v23, vcc, 0, v21, vcc
	global_load_dword v39, v[22:23], off
	v_add_co_u32_e32 v22, vcc, s4, v20
	s_mov_b32 s4, 0x24000
	s_nop 0
	v_addc_co_u32_e32 v23, vcc, 0, v21, vcc
	global_load_dword v40, v[22:23], off
	v_add_co_u32_e32 v22, vcc, s4, v20
	s_mov_b32 s4, 0x26000
	s_nop 0
	v_addc_co_u32_e32 v23, vcc, 0, v21, vcc
	global_load_dword v41, v[22:23], off
	v_add_co_u32_e32 v22, vcc, s4, v20
	s_mov_b32 s4, 0x28000
	s_nop 0
	v_addc_co_u32_e32 v23, vcc, 0, v21, vcc
	global_load_dword v91, v[22:23], off
	v_add_co_u32_e32 v22, vcc, s4, v20
	s_mov_b32 s4, 0x2a000
	s_nop 0
	v_addc_co_u32_e32 v23, vcc, 0, v21, vcc
	global_load_dword v92, v[22:23], off
	v_add_co_u32_e32 v22, vcc, s4, v20
	s_mov_b32 s4, 0x2c000
	s_nop 0
	v_addc_co_u32_e32 v23, vcc, 0, v21, vcc
	global_load_dword v93, v[22:23], off
	v_add_co_u32_e32 v22, vcc, s4, v20
	s_mov_b32 s4, 0x2e000
	s_nop 0
	v_addc_co_u32_e32 v23, vcc, 0, v21, vcc
	global_load_dword v94, v[22:23], off
	v_add_co_u32_e32 v22, vcc, s4, v20
	s_mov_b32 s4, 0x30000
	s_nop 0
	v_addc_co_u32_e32 v23, vcc, 0, v21, vcc
	global_load_dword v95, v[22:23], off
	v_add_co_u32_e32 v22, vcc, s4, v20
	s_mov_b32 s4, 0x32000
	s_nop 0
	v_addc_co_u32_e32 v23, vcc, 0, v21, vcc
	global_load_dword v96, v[22:23], off
	v_add_co_u32_e32 v22, vcc, s4, v20
	s_mov_b32 s4, 0x34000
	s_nop 0
	v_addc_co_u32_e32 v23, vcc, 0, v21, vcc
	global_load_dword v97, v[22:23], off
	v_add_co_u32_e32 v22, vcc, s4, v20
	s_mov_b32 s4, 0x36000
	s_nop 0
	v_addc_co_u32_e32 v23, vcc, 0, v21, vcc
	global_load_dword v98, v[22:23], off
	v_add_co_u32_e32 v22, vcc, s4, v20
	s_mov_b32 s4, 0x38000
	s_nop 0
	v_addc_co_u32_e32 v23, vcc, 0, v21, vcc
	global_load_dword v99, v[22:23], off
	v_add_co_u32_e32 v22, vcc, s4, v20
	s_mov_b32 s4, 0x3a000
	s_nop 0
	v_addc_co_u32_e32 v23, vcc, 0, v21, vcc
	global_load_dword v100, v[22:23], off
	v_add_co_u32_e32 v22, vcc, s4, v20
	s_mov_b32 s4, 0x3c000
	s_nop 0
	v_addc_co_u32_e32 v23, vcc, 0, v21, vcc
	global_load_dword v101, v[22:23], off
	v_add_co_u32_e32 v22, vcc, s4, v20
	s_mov_b32 s4, 0x3e000
	s_nop 0
	v_addc_co_u32_e32 v23, vcc, 0, v21, vcc
	v_add_co_u32_e32 v20, vcc, s4, v20
	global_load_dword v22, v[22:23], off
	s_nop 0
	v_addc_co_u32_e32 v21, vcc, 0, v21, vcc
	global_load_dword v20, v[20:21], off
	s_waitcnt vmcnt(0)
; #define LAS __attribute__((address_space(3)))
; __device__ __forceinline__ unsigned cvt_pk_bf16(float lo, float hi) { unsigned r; asm volatile("v_cvt_pk_bf16_f32 %0, %1, %2" : "=v"(r) : "v"(lo), "v"(hi)); return r; }
; __device__ __forceinline__ void wconv_item(const float* W, int K, int Norig, int Nphys, bf16_t* WT, const float* gA, const float* gB, int split, int mapid, LAS float* scr, int item, int lane) {
;     ...
;     for (int i = 0; i < 32; ++i) { const int kk = 2 * i + (lane >> 5), k = k0 + kk;
;         float v = wv[i];
;         if (gA) v *= (k < split ? gA[k] : gB[k - split]);
;         scr[kk * 33 + (lane & 31)] = v; }
;     asm volatile("s_waitcnt lgkmcnt(0)" ::: "memory");
;     const int c = lane & 7;
; #pragma unroll
;     for (int j = 0; j < 4; ++j) { const int n = (lane >> 3) + 8 * j; const LAS float* s = scr + (8 * c) * 33 + n;
;         u32x4 o; o.x = cvt_pk_bf16(s[0 * 33], s[1 * 33]); o.y = cvt_pk_bf16(s[2 * 33], s[3 * 33]); o.z = cvt_pk_bf16(s[4 * 33], s[5 * 33]); o.w = cvt_pk_bf16(s[6 * 33], s[7 * 33]);
;         *(u32x4*)(WT + (size_t)(n0 + n) * K + k0 + 8 * c) = o; }
;     asm volatile("s_waitcnt lgkmcnt(0)" ::: "memory");
	ds_write2_b32 v44, v0, v24 offset1:66
	ds_write2_b32 v44, v25, v26 offset0:132 offset1:198
	v_add_u32_e32 v0, 0x400, v44
	ds_write2_b32 v0, v27, v28 offset0:8 offset1:74
	ds_write2_b32 v0, v29, v30 offset0:140 offset1:206
	v_add_u32_e32 v0, 0x800, v44
	ds_write2_b32 v0, v31, v32 offset0:16 offset1:82
	ds_write2_b32 v0, v33, v34 offset0:148 offset1:214
	v_add_u32_e32 v0, 0xc00, v44
	ds_write2_b32 v0, v35, v36 offset0:24 offset1:90
	ds_write2_b32 v0, v37, v38 offset0:156 offset1:222
	v_add_u32_e32 v0, 0x1000, v44
	ds_write2_b32 v0, v39, v40 offset0:32 offset1:98
	ds_write2_b32 v0, v41, v91 offset0:164 offset1:230
	v_add_u32_e32 v0, 0x1400, v44
	ds_write2_b32 v0, v92, v93 offset0:40 offset1:106
	ds_write2_b32 v0, v94, v95 offset0:172 offset1:238
	v_add_u32_e32 v0, 0x1800, v44
	ds_write2_b32 v0, v96, v97 offset0:48 offset1:114
	ds_write2_b32 v0, v98, v99 offset0:180 offset1:246
	v_add_u32_e32 v0, 0x1c00, v44
	ds_write2_b32 v0, v100, v101 offset0:56 offset1:122
	ds_write2_b32 v0, v22, v20 offset0:188 offset1:254
	s_waitcnt lgkmcnt(0)
	ds_read2_b32 v[20:21], v46 offset1:33
	s_waitcnt lgkmcnt(0)
	v_cvt_pk_bf16_f32 v20, v20, v21
	ds_read2_b32 v[22:23], v46 offset0:66 offset1:99
	s_waitcnt lgkmcnt(0)
	v_cvt_pk_bf16_f32 v21, v22, v23
	ds_read2_b32 v[22:23], v46 offset0:132 offset1:165
	v_or_b32_e32 v0, s38, v45
	v_lshl_add_u64 v[24:25], v[4:5], 0, s[48:49]
	s_waitcnt lgkmcnt(0)
	v_cvt_pk_bf16_f32 v22, v22, v23
	ds_read2_b32 v[26:27], v46 offset0:198 offset1:231
	v_lshlrev_b32_e32 v0, 9, v0
	s_waitcnt lgkmcnt(0)
	v_cvt_pk_bf16_f32 v23, v26, v27
	v_lshl_add_u64 v[26:27], v[24:25], 0, v[0:1]
	global_store_dwordx4 v[26:27], v[20:23], off sc1
	ds_read2_b32 v[20:21], v46 offset0:8 offset1:41
	v_or_b32_e32 v0, s38, v47
	s_waitcnt lgkmcnt(0)
	v_cvt_pk_bf16_f32 v20, v20, v21
	ds_read2_b32 v[22:23], v46 offset0:74 offset1:107
	s_waitcnt lgkmcnt(0)
	v_cvt_pk_bf16_f32 v21, v22, v23
	ds_read2_b32 v[22:23], v46 offset0:140 offset1:173
	s_waitcnt lgkmcnt(0)
	v_cvt_pk_bf16_f32 v22, v22, v23
	ds_read2_b32 v[26:27], v46 offset0:206 offset1:239
	v_lshlrev_b32_e32 v0, 9, v0
	s_waitcnt lgkmcnt(0)
	v_cvt_pk_bf16_f32 v23, v26, v27
	v_lshl_add_u64 v[26:27], v[24:25], 0, v[0:1]
	global_store_dwordx4 v[26:27], v[20:23], off sc1
	ds_read2_b32 v[20:21], v46 offset0:16 offset1:49
	v_or_b32_e32 v0, s38, v48
	s_waitcnt lgkmcnt(0)
	v_cvt_pk_bf16_f32 v20, v20, v21
	ds_read2_b32 v[22:23], v46 offset0:82 offset1:115
	s_waitcnt lgkmcnt(0)
	v_cvt_pk_bf16_f32 v21, v22, v23
	ds_read2_b32 v[22:23], v46 offset0:148 offset1:181
	s_waitcnt lgkmcnt(0)
	v_cvt_pk_bf16_f32 v22, v22, v23
	ds_read2_b32 v[26:27], v46 offset0:214 offset1:247
	v_lshlrev_b32_e32 v0, 9, v0
	s_waitcnt lgkmcnt(0)
	v_cvt_pk_bf16_f32 v23, v26, v27
	v_lshl_add_u64 v[26:27], v[24:25], 0, v[0:1]
	global_store_dwordx4 v[26:27], v[20:23], off sc1
	ds_read2_b32 v[20:21], v46 offset0:24 offset1:57
	v_or_b32_e32 v0, s38, v49
	s_waitcnt lgkmcnt(0)
	v_cvt_pk_bf16_f32 v20, v20, v21
	ds_read2_b32 v[22:23], v46 offset0:90 offset1:123
	v_lshlrev_b32_e32 v0, 9, v0
	s_waitcnt lgkmcnt(0)
	v_cvt_pk_bf16_f32 v21, v22, v23
	ds_read2_b32 v[22:23], v46 offset0:156 offset1:189
	v_lshl_add_u64 v[24:25], v[24:25], 0, v[0:1]
	s_waitcnt lgkmcnt(0)
	v_cvt_pk_bf16_f32 v22, v22, v23
	ds_read2_b32 v[26:27], v46 offset0:222 offset1:255
	s_waitcnt lgkmcnt(0)
	v_cvt_pk_bf16_f32 v23, v26, v27
	global_store_dwordx4 v[24:25], v[20:23], off sc1
	s_waitcnt lgkmcnt(0)
	s_mov_b64 s[38:39], 0

; #define LAS __attribute__((address_space(3)))
; __device__ __forceinline__ unsigned cvt_pk_bf16(float lo, float hi) { unsigned r; asm volatile("v_cvt_pk_bf16_f32 %0, %1, %2" : "=v"(r) : "v"(lo), "v"(hi)); return r; }
; __device__ __forceinline__ void wconv_item(const float* W, int K, int Norig, int Nphys, bf16_t* WT, const float* gA, const float* gB, int split, int mapid, LAS float* scr, int item, int lane) {
;     ...
;     for (int i = 0; i < 32; ++i) { const int kk = 2 * i + (lane >> 5), k = k0 + kk;
;         float v = wv[i];
;         if (gA) v *= (k < split ? gA[k] : gB[k - split]);
;         scr[kk * 33 + (lane & 31)] = v; }
;     asm volatile("s_waitcnt lgkmcnt(0)" ::: "memory");
;     const int c = lane & 7;
; #pragma unroll
;     for (int j = 0; j < 4; ++j) { const int n = (lane >> 3) + 8 * j; const LAS float* s = scr + (8 * c) * 33 + n;
;         u32x4 o; o.x = cvt_pk_bf16(s[0 * 33], s[1 * 33]); o.y = cvt_pk_bf16(s[2 * 33], s[3 * 33]); o.z = cvt_pk_bf16(s[4 * 33], s[5 * 33]); o.w = cvt_pk_bf16(s[6 * 33], s[7 * 33]);
;         *(u32x4*)(WT + (size_t)(n0 + n) * K + k0 + 8 * c) = o; }
;     asm volatile("s_waitcnt lgkmcnt(0)" ::: "memory");
.LBB0_1087:
	v_add_u32_e32 v0, v43, v80
	v_add_u32_e32 v0, 0x400, v0
	ds_write2_b32 v0, v24, v25 offset0:8 offset1:74
	ds_write2_b32 v0, v26, v27 offset0:140 offset1:206
	s_waitcnt lgkmcnt(0)
	ds_read2_b32 v[20:21], v46 offset1:33
	s_waitcnt lgkmcnt(0)
	v_cvt_pk_bf16_f32 v20, v20, v21
	ds_read2_b32 v[22:23], v46 offset0:66 offset1:99
	s_lshl_b32 s48, s48, 1
	s_waitcnt lgkmcnt(0)
	v_cvt_pk_bf16_f32 v21, v22, v23
	ds_read2_b32 v[22:23], v46 offset0:132 offset1:165
	v_or_b32_e32 v0, s72, v45
	v_lshl_add_u64 v[24:25], v[6:7], 0, s[48:49]
	s_waitcnt lgkmcnt(0)
	v_cvt_pk_bf16_f32 v22, v22, v23
	ds_read2_b32 v[26:27], v46 offset0:198 offset1:231
	v_lshlrev_b32_e32 v0, 11, v0
	s_waitcnt lgkmcnt(0)
	v_cvt_pk_bf16_f32 v23, v26, v27
	v_lshl_add_u64 v[26:27], v[24:25], 0, v[0:1]
	global_store_dwordx4 v[26:27], v[20:23], off sc1
	ds_read2_b32 v[20:21], v46 offset0:8 offset1:41
	v_or_b32_e32 v0, s72, v47
	s_waitcnt lgkmcnt(0)
	v_cvt_pk_bf16_f32 v20, v20, v21
	ds_read2_b32 v[22:23], v46 offset0:74 offset1:107
	s_waitcnt lgkmcnt(0)
	v_cvt_pk_bf16_f32 v21, v22, v23
	ds_read2_b32 v[22:23], v46 offset0:140 offset1:173
	s_waitcnt lgkmcnt(0)
	v_cvt_pk_bf16_f32 v22, v22, v23
	ds_read2_b32 v[26:27], v46 offset0:206 offset1:239
	v_lshlrev_b32_e32 v0, 11, v0
	s_waitcnt lgkmcnt(0)
	v_cvt_pk_bf16_f32 v23, v26, v27
	v_lshl_add_u64 v[26:27], v[24:25], 0, v[0:1]
	global_store_dwordx4 v[26:27], v[20:23], off sc1
	ds_read2_b32 v[20:21], v46 offset0:16 offset1:49
	v_or_b32_e32 v0, s72, v48
	s_waitcnt lgkmcnt(0)
	v_cvt_pk_bf16_f32 v20, v20, v21
	ds_read2_b32 v[22:23], v46 offset0:82 offset1:115
	s_waitcnt lgkmcnt(0)
	v_cvt_pk_bf16_f32 v21, v22, v23
	ds_read2_b32 v[22:23], v46 offset0:148 offset1:181
	s_waitcnt lgkmcnt(0)
	v_cvt_pk_bf16_f32 v22, v22, v23
	ds_read2_b32 v[26:27], v46 offset0:214 offset1:247
	v_lshlrev_b32_e32 v0, 11, v0
	s_waitcnt lgkmcnt(0)
	v_cvt_pk_bf16_f32 v23, v26, v27
	v_lshl_add_u64 v[26:27], v[24:25], 0, v[0:1]
	global_store_dwordx4 v[26:27], v[20:23], off sc1
	ds_read2_b32 v[20:21], v46 offset0:24 offset1:57
	v_or_b32_e32 v0, s72, v49
	s_waitcnt lgkmcnt(0)
	v_cvt_pk_bf16_f32 v20, v20, v21
	ds_read2_b32 v[22:23], v46 offset0:90 offset1:123
	v_lshlrev_b32_e32 v0, 11, v0
	s_waitcnt lgkmcnt(0)
	v_cvt_pk_bf16_f32 v21, v22, v23
	ds_read2_b32 v[22:23], v46 offset0:156 offset1:189
	v_lshl_add_u64 v[24:25], v[24:25], 0, v[0:1]
	s_waitcnt lgkmcnt(0)
	v_cvt_pk_bf16_f32 v22, v22, v23
	ds_read2_b32 v[26:27], v46 offset0:222 offset1:255
	s_waitcnt lgkmcnt(0)
	v_cvt_pk_bf16_f32 v23, v26, v27
	global_store_dwordx4 v[24:25], v[20:23], off sc1
	s_waitcnt lgkmcnt(0)

; __device__ __forceinline__ void wconv_item(const float* W, int K, int Norig, int Nphys, bf16_t* WT, const float* gA, const float* gB, int split, int mapid, LAS float* scr, int item, int lane) {
;     const int nblk = Nphys / 32, kb = item / nblk, nb = item % nblk, k0 = 64 * kb, n0 = 32 * nb;
;     const int norig = colmap(mapid, n0 + (lane & 31));
;     float wv[32];
; #pragma unroll
;     for (int i = 0; i < 32; ++i) { const int k = k0 + 2 * i + (lane >> 5); wv[i] = (norig >= 0) ? W[(size_t)k * Norig + norig] : 0.f; }
; template <class AP> __device__ __forceinline__ void convert_weights(AP a, int L, bf16_t* wb, LAS float* scr, int gw, int NGW, int lane) {
;     ...
;     for (int it = gw; it < NIT; it += NGW) {
;         int r = it;
;         if (r < I0) { wconv_item(w_in, 1024, INC, INP, wb + WO_IN, g_mix, g_mix, 1024, 0, scr, r, lane); continue; } r -= I0;
;         if (r < I1) { wconv_item(w_uq, QL, 768, 768, wb + WO_UQ, g_ql, g_ql, QL, 1, scr, r, lane); continue; } r -= I1;
;         if (r < I2) { wconv_item(w_ukv, KVL, 1024, 1024, wb + WO_UKV, g_kvl, g_kvl, KVL, 2, scr, r, lane); continue; } r -= I2;
;         if (r < I3) { wconv_item(w_o, 1024, 1024, 1024, wb + WO_O, g_oa, g_oc, 512, 3, scr, r, lane); continue; } r -= I3;
;         if (r < I4) { wconv_item(w_up, 1024, FF, FF, wb + WO_UP, g_mlp, g_mlp, 1024, 3, scr, r, lane); continue; } r -= I4;
;         if (r < I5) { wconv_item(w_dn, FF, 1024, 1024, wb + WO_DN, nullptr, nullptr, 0, 3, scr, r, lane); continue; } r -= I5;
;         if (r < I6) { wconv_item(w_g, 1024, 1024, 1024, wb + WO_G, g_ple, g_ple, 1024, 3, scr, r, lane); continue; } r -= I6;
;         wconv_item(w_ple, PLE, 1024, 1024, wb + WO_PLE, nullptr, nullptr, 0, 3, scr, r, lane);
.LBB0_1089:
	s_andn2_b64 vcc, exec, s[38:39]
	s_cbranch_vccnz .LBB0_1091
	s_add_i32 s4, s84, 0x1400
	s_and_b32 s39, s4, 0x1ffc0
	s_add_i32 s4, s82, 0xfffe0e00
	s_and_b32 s38, s4, 0x3e0
	v_or_b32_e32 v0, s38, v42
	v_or_b32_e32 v22, s39, v2
	v_lshlrev_b32_e32 v0, 2, v0
	v_lshl_add_u64 v[20:21], s[88:89], 0, v[0:1]
	v_lshlrev_b32_e32 v0, 12, v22
	v_lshl_add_u64 v[20:21], v[20:21], 0, v[0:1]
	v_add_co_u32_e32 v22, vcc, 0x2000, v20
	global_load_dword v0, v[20:21], off
	s_nop 0
	v_addc_co_u32_e32 v23, vcc, 0, v21, vcc
	global_load_dword v24, v[22:23], off
	v_add_co_u32_e32 v22, vcc, 0x4000, v20
	s_mov_b32 s4, 0x10000
	s_nop 0
	v_addc_co_u32_e32 v23, vcc, 0, v21, vcc
	global_load_dword v25, v[22:23], off
	v_add_co_u32_e32 v22, vcc, 0x6000, v20
	s_lshl_b32 s48, s39, 1
	s_nop 0
	v_addc_co_u32_e32 v23, vcc, 0, v21, vcc
	global_load_dword v26, v[22:23], off
	v_add_co_u32_e32 v22, vcc, 0x8000, v20
	s_nop 1
	v_addc_co_u32_e32 v23, vcc, 0, v21, vcc
	global_load_dword v27, v[22:23], off
	v_add_co_u32_e32 v22, vcc, 0xa000, v20
	s_nop 1
	v_addc_co_u32_e32 v23, vcc, 0, v21, vcc
	global_load_dword v28, v[22:23], off
	v_add_co_u32_e32 v22, vcc, 0xc000, v20
	s_nop 1
	v_addc_co_u32_e32 v23, vcc, 0, v21, vcc
	global_load_dword v29, v[22:23], off
	v_add_co_u32_e32 v22, vcc, 0xe000, v20
	s_nop 1
	v_addc_co_u32_e32 v23, vcc, 0, v21, vcc
	global_load_dword v30, v[22:23], off
	v_add_co_u32_e32 v22, vcc, s4, v20
	s_mov_b32 s4, 0x12000
	s_nop 0
	v_addc_co_u32_e32 v23, vcc, 0, v21, vcc
	global_load_dword v31, v[22:23], off
	v_add_co_u32_e32 v22, vcc, s4, v20
	s_mov_b32 s4, 0x14000
	s_nop 0
	v_addc_co_u32_e32 v23, vcc, 0, v21, vcc
	global_load_dword v32, v[22:23], off
	v_add_co_u32_e32 v22, vcc, s4, v20
	s_mov_b32 s4, 0x16000
	s_nop 0
	v_addc_co_u32_e32 v23, vcc, 0, v21, vcc
	global_load_dword v33, v[22:23], off
	v_add_co_u32_e32 v22, vcc, s4, v20
	s_mov_b32 s4, 0x18000
	s_nop 0
	v_addc_co_u32_e32 v23, vcc, 0, v21, vcc
	global_load_dword v34, v[22:23], off
	v_add_co_u32_e32 v22, vcc, s4, v20
	s_mov_b32 s4, 0x1a000
	s_nop 0
	v_addc_co_u32_e32 v23, vcc, 0, v21, vcc
	global_load_dword v35, v[22:23], off
	v_add_co_u32_e32 v22, vcc, s4, v20
	s_mov_b32 s4, 0x1c000
	s_nop 0
	v_addc_co_u32_e32 v23, vcc, 0, v21, vcc
	global_load_dword v36, v[22:23], off
	v_add_co_u32_e32 v22, vcc, s4, v20
	s_mov_b32 s4, 0x1e000
	s_nop 0
	v_addc_co_u32_e32 v23, vcc, 0, v21, vcc
	global_load_dword v37, v[22:23], off
	v_add_co_u32_e32 v22, vcc, s4, v20
	s_mov_b32 s4, 0x20000
	s_nop 0
	v_addc_co_u32_e32 v23, vcc, 0, v21, vcc
	global_load_dword v38, v[22:23], off
	v_add_co_u32_e32 v22, vcc, s4, v20
	s_mov_b32 s4, 0x22000
	s_nop 0
	v_addc_co_u32_e32 v23, vcc, 0, v21, vcc
	global_load_dword v39, v[22:23], off
	v_add_co_u32_e32 v22, vcc, s4, v20
	s_mov_b32 s4, 0x24000
	s_nop 0
	v_addc_co_u32_e32 v23, vcc, 0, v21, vcc
	global_load_dword v40, v[22:23], off
	v_add_co_u32_e32 v22, vcc, s4, v20
	s_mov_b32 s4, 0x26000
	s_nop 0
	v_addc_co_u32_e32 v23, vcc, 0, v21, vcc
	global_load_dword v41, v[22:23], off
	v_add_co_u32_e32 v22, vcc, s4, v20
	s_mov_b32 s4, 0x28000
	s_nop 0
	v_addc_co_u32_e32 v23, vcc, 0, v21, vcc
	global_load_dword v91, v[22:23], off
	v_add_co_u32_e32 v22, vcc, s4, v20
	s_mov_b32 s4, 0x2a000
	s_nop 0
	v_addc_co_u32_e32 v23, vcc, 0, v21, vcc
	global_load_dword v92, v[22:23], off
	v_add_co_u32_e32 v22, vcc, s4, v20
	s_mov_b32 s4, 0x2c000
	s_nop 0
	v_addc_co_u32_e32 v23, vcc, 0, v21, vcc
	global_load_dword v93, v[22:23], off
	v_add_co_u32_e32 v22, vcc, s4, v20
	s_mov_b32 s4, 0x2e000
	s_nop 0
	v_addc_co_u32_e32 v23, vcc, 0, v21, vcc
	global_load_dword v94, v[22:23], off
	v_add_co_u32_e32 v22, vcc, s4, v20
	s_mov_b32 s4, 0x30000
	s_nop 0
	v_addc_co_u32_e32 v23, vcc, 0, v21, vcc
	global_load_dword v95, v[22:23], off
	v_add_co_u32_e32 v22, vcc, s4, v20
	s_mov_b32 s4, 0x32000
	s_nop 0
	v_addc_co_u32_e32 v23, vcc, 0, v21, vcc
	global_load_dword v96, v[22:23], off
	v_add_co_u32_e32 v22, vcc, s4, v20
	s_mov_b32 s4, 0x34000
	s_nop 0
	v_addc_co_u32_e32 v23, vcc, 0, v21, vcc
	global_load_dword v97, v[22:23], off
	v_add_co_u32_e32 v22, vcc, s4, v20
	s_mov_b32 s4, 0x36000
	s_nop 0
	v_addc_co_u32_e32 v23, vcc, 0, v21, vcc
	global_load_dword v98, v[22:23], off
	v_add_co_u32_e32 v22, vcc, s4, v20
	s_mov_b32 s4, 0x38000
	s_nop 0
	v_addc_co_u32_e32 v23, vcc, 0, v21, vcc
	global_load_dword v99, v[22:23], off
	v_add_co_u32_e32 v22, vcc, s4, v20
	s_mov_b32 s4, 0x3a000
	s_nop 0
	v_addc_co_u32_e32 v23, vcc, 0, v21, vcc
	global_load_dword v100, v[22:23], off
	v_add_co_u32_e32 v22, vcc, s4, v20
	s_mov_b32 s4, 0x3c000
	s_nop 0
	v_addc_co_u32_e32 v23, vcc, 0, v21, vcc
	global_load_dword v101, v[22:23], off
	v_add_co_u32_e32 v22, vcc, s4, v20
	s_mov_b32 s4, 0x3e000
	s_nop 0
	v_addc_co_u32_e32 v23, vcc, 0, v21, vcc
	v_add_co_u32_e32 v20, vcc, s4, v20
	global_load_dword v22, v[22:23], off
	s_nop 0
	v_addc_co_u32_e32 v21, vcc, 0, v21, vcc
	global_load_dword v20, v[20:21], off
	s_waitcnt vmcnt(0)
; #define LAS __attribute__((address_space(3)))
; __device__ __forceinline__ unsigned cvt_pk_bf16(float lo, float hi) { unsigned r; asm volatile("v_cvt_pk_bf16_f32 %0, %1, %2" : "=v"(r) : "v"(lo), "v"(hi)); return r; }
; __device__ __forceinline__ void wconv_item(const float* W, int K, int Norig, int Nphys, bf16_t* WT, const float* gA, const float* gB, int split, int mapid, LAS float* scr, int item, int lane) {
;     ...
;     for (int i = 0; i < 32; ++i) { const int kk = 2 * i + (lane >> 5), k = k0 + kk;
;         float v = wv[i];
;         if (gA) v *= (k < split ? gA[k] : gB[k - split]);
;         scr[kk * 33 + (lane & 31)] = v; }
;     asm volatile("s_waitcnt lgkmcnt(0)" ::: "memory");
;     const int c = lane & 7;
; #pragma unroll
;     for (int j = 0; j < 4; ++j) { const int n = (lane >> 3) + 8 * j; const LAS float* s = scr + (8 * c) * 33 + n;
;         u32x4 o; o.x = cvt_pk_bf16(s[0 * 33], s[1 * 33]); o.y = cvt_pk_bf16(s[2 * 33], s[3 * 33]); o.z = cvt_pk_bf16(s[4 * 33], s[5 * 33]); o.w = cvt_pk_bf16(s[6 * 33], s[7 * 33]);
;         *(u32x4*)(WT + (size_t)(n0 + n) * K + k0 + 8 * c) = o; }
;     asm volatile("s_waitcnt lgkmcnt(0)" ::: "memory");
	ds_write2_b32 v44, v0, v24 offset1:66
	ds_write2_b32 v44, v25, v26 offset0:132 offset1:198
	v_add_u32_e32 v0, 0x400, v44
	ds_write2_b32 v0, v27, v28 offset0:8 offset1:74
	ds_write2_b32 v0, v29, v30 offset0:140 offset1:206
	v_add_u32_e32 v0, 0x800, v44
	ds_write2_b32 v0, v31, v32 offset0:16 offset1:82
	ds_write2_b32 v0, v33, v34 offset0:148 offset1:214
	v_add_u32_e32 v0, 0xc00, v44
	ds_write2_b32 v0, v35, v36 offset0:24 offset1:90
	ds_write2_b32 v0, v37, v38 offset0:156 offset1:222
	v_add_u32_e32 v0, 0x1000, v44
	ds_write2_b32 v0, v39, v40 offset0:32 offset1:98
	ds_write2_b32 v0, v41, v91 offset0:164 offset1:230
	v_add_u32_e32 v0, 0x1400, v44
	ds_write2_b32 v0, v92, v93 offset0:40 offset1:106
	ds_write2_b32 v0, v94, v95 offset0:172 offset1:238
	v_add_u32_e32 v0, 0x1800, v44
	ds_write2_b32 v0, v96, v97 offset0:48 offset1:114
	ds_write2_b32 v0, v98, v99 offset0:180 offset1:246
	v_add_u32_e32 v0, 0x1c00, v44
	ds_write2_b32 v0, v100, v101 offset0:56 offset1:122
	ds_write2_b32 v0, v22, v20 offset0:188 offset1:254
	s_waitcnt lgkmcnt(0)
	ds_read2_b32 v[20:21], v46 offset1:33
	s_waitcnt lgkmcnt(0)
	v_cvt_pk_bf16_f32 v20, v20, v21
	ds_read2_b32 v[22:23], v46 offset0:66 offset1:99
	s_waitcnt lgkmcnt(0)
	v_cvt_pk_bf16_f32 v21, v22, v23
	ds_read2_b32 v[22:23], v46 offset0:132 offset1:165
	v_or_b32_e32 v0, s38, v45
	v_lshl_add_u64 v[24:25], v[8:9], 0, s[48:49]
	s_waitcnt lgkmcnt(0)
	v_cvt_pk_bf16_f32 v22, v22, v23
	ds_read2_b32 v[26:27], v46 offset0:198 offset1:231
	v_lshlrev_b32_e32 v0, 13, v0
	s_waitcnt lgkmcnt(0)
	v_cvt_pk_bf16_f32 v23, v26, v27
	v_lshl_add_u64 v[26:27], v[24:25], 0, v[0:1]
	global_store_dwordx4 v[26:27], v[20:23], off sc1
	ds_read2_b32 v[20:21], v46 offset0:8 offset1:41
	v_or_b32_e32 v0, s38, v47
	s_waitcnt lgkmcnt(0)
	v_cvt_pk_bf16_f32 v20, v20, v21
	ds_read2_b32 v[22:23], v46 offset0:74 offset1:107
	s_waitcnt lgkmcnt(0)
	v_cvt_pk_bf16_f32 v21, v22, v23
	ds_read2_b32 v[22:23], v46 offset0:140 offset1:173
	s_waitcnt lgkmcnt(0)
	v_cvt_pk_bf16_f32 v22, v22, v23
	ds_read2_b32 v[26:27], v46 offset0:206 offset1:239
	v_lshlrev_b32_e32 v0, 13, v0
	s_waitcnt lgkmcnt(0)
	v_cvt_pk_bf16_f32 v23, v26, v27
	v_lshl_add_u64 v[26:27], v[24:25], 0, v[0:1]
	global_store_dwordx4 v[26:27], v[20:23], off sc1
	ds_read2_b32 v[20:21], v46 offset0:16 offset1:49
	v_or_b32_e32 v0, s38, v48
	s_waitcnt lgkmcnt(0)
	v_cvt_pk_bf16_f32 v20, v20, v21
	ds_read2_b32 v[22:23], v46 offset0:82 offset1:115
	s_waitcnt lgkmcnt(0)
	v_cvt_pk_bf16_f32 v21, v22, v23
	ds_read2_b32 v[22:23], v46 offset0:148 offset1:181
	s_waitcnt lgkmcnt(0)
	v_cvt_pk_bf16_f32 v22, v22, v23
	ds_read2_b32 v[26:27], v46 offset0:214 offset1:247
	v_lshlrev_b32_e32 v0, 13, v0
	s_waitcnt lgkmcnt(0)
	v_cvt_pk_bf16_f32 v23, v26, v27
	v_lshl_add_u64 v[26:27], v[24:25], 0, v[0:1]
	global_store_dwordx4 v[26:27], v[20:23], off sc1
	ds_read2_b32 v[20:21], v46 offset0:24 offset1:57
	v_or_b32_e32 v0, s38, v49
	s_waitcnt lgkmcnt(0)
	v_cvt_pk_bf16_f32 v20, v20, v21
	ds_read2_b32 v[22:23], v46 offset0:90 offset1:123
	v_lshlrev_b32_e32 v0, 13, v0
	s_waitcnt lgkmcnt(0)
	v_cvt_pk_bf16_f32 v21, v22, v23
	ds_read2_b32 v[22:23], v46 offset0:156 offset1:189
	v_lshl_add_u64 v[24:25], v[24:25], 0, v[0:1]
	s_waitcnt lgkmcnt(0)
	v_cvt_pk_bf16_f32 v22, v22, v23
	ds_read2_b32 v[26:27], v46 offset0:222 offset1:255
	s_waitcnt lgkmcnt(0)
	v_cvt_pk_bf16_f32 v23, v26, v27
	global_store_dwordx4 v[24:25], v[20:23], off sc1
	s_waitcnt lgkmcnt(0)

; #define LAS __attribute__((address_space(3)))
; __device__ __forceinline__ unsigned cvt_pk_bf16(float lo, float hi) { unsigned r; asm volatile("v_cvt_pk_bf16_f32 %0, %1, %2" : "=v"(r) : "v"(lo), "v"(hi)); return r; }
; __device__ __forceinline__ void wconv_item(const float* W, int K, int Norig, int Nphys, bf16_t* WT, const float* gA, const float* gB, int split, int mapid, LAS float* scr, int item, int lane) {
;     ...
;     for (int i = 0; i < 32; ++i) { const int kk = 2 * i + (lane >> 5), k = k0 + kk;
;         float v = wv[i];
;         if (gA) v *= (k < split ? gA[k] : gB[k - split]);
;         scr[kk * 33 + (lane & 31)] = v; }
;     asm volatile("s_waitcnt lgkmcnt(0)" ::: "memory");
;     const int c = lane & 7;
; #pragma unroll
;     for (int j = 0; j < 4; ++j) { const int n = (lane >> 3) + 8 * j; const LAS float* s = scr + (8 * c) * 33 + n;
;         u32x4 o; o.x = cvt_pk_bf16(s[0 * 33], s[1 * 33]); o.y = cvt_pk_bf16(s[2 * 33], s[3 * 33]); o.z = cvt_pk_bf16(s[4 * 33], s[5 * 33]); o.w = cvt_pk_bf16(s[6 * 33], s[7 * 33]);
;         *(u32x4*)(WT + (size_t)(n0 + n) * K + k0 + 8 * c) = o; }
;     asm volatile("s_waitcnt lgkmcnt(0)" ::: "memory");
.LBB0_1105:
	v_add_u32_e32 v0, v43, v80
	v_add_u32_e32 v0, 0x400, v0
	ds_write2_b32 v0, v24, v25 offset0:8 offset1:74
	ds_write2_b32 v0, v26, v27 offset0:140 offset1:206
	s_waitcnt lgkmcnt(0)
	ds_read2_b32 v[20:21], v46 offset1:33
	s_waitcnt lgkmcnt(0)
	v_cvt_pk_bf16_f32 v20, v20, v21
	ds_read2_b32 v[22:23], v46 offset0:66 offset1:99
	s_lshl_b32 s48, s48, 1
	s_waitcnt lgkmcnt(0)
	v_cvt_pk_bf16_f32 v21, v22, v23
	ds_read2_b32 v[22:23], v46 offset0:132 offset1:165
	v_or_b32_e32 v0, s72, v45
	v_lshl_add_u64 v[24:25], v[10:11], 0, s[48:49]
	s_waitcnt lgkmcnt(0)
	v_cvt_pk_bf16_f32 v22, v22, v23
	ds_read2_b32 v[26:27], v46 offset0:198 offset1:231
	v_lshlrev_b32_e32 v0, 11, v0
	s_waitcnt lgkmcnt(0)
	v_cvt_pk_bf16_f32 v23, v26, v27
	v_lshl_add_u64 v[26:27], v[24:25], 0, v[0:1]
	global_store_dwordx4 v[26:27], v[20:23], off sc1
	ds_read2_b32 v[20:21], v46 offset0:8 offset1:41
	v_or_b32_e32 v0, s72, v47
	s_waitcnt lgkmcnt(0)
	v_cvt_pk_bf16_f32 v20, v20, v21
	ds_read2_b32 v[22:23], v46 offset0:74 offset1:107
	s_waitcnt lgkmcnt(0)
	v_cvt_pk_bf16_f32 v21, v22, v23
	ds_read2_b32 v[22:23], v46 offset0:140 offset1:173
	s_waitcnt lgkmcnt(0)
	v_cvt_pk_bf16_f32 v22, v22, v23
	ds_read2_b32 v[26:27], v46 offset0:206 offset1:239
	v_lshlrev_b32_e32 v0, 11, v0
	s_waitcnt lgkmcnt(0)
	v_cvt_pk_bf16_f32 v23, v26, v27
	v_lshl_add_u64 v[26:27], v[24:25], 0, v[0:1]
	global_store_dwordx4 v[26:27], v[20:23], off sc1
	ds_read2_b32 v[20:21], v46 offset0:16 offset1:49
	v_or_b32_e32 v0, s72, v48
	s_waitcnt lgkmcnt(0)
	v_cvt_pk_bf16_f32 v20, v20, v21
	ds_read2_b32 v[22:23], v46 offset0:82 offset1:115
	s_waitcnt lgkmcnt(0)
	v_cvt_pk_bf16_f32 v21, v22, v23
	ds_read2_b32 v[22:23], v46 offset0:148 offset1:181
	s_waitcnt lgkmcnt(0)
	v_cvt_pk_bf16_f32 v22, v22, v23
	ds_read2_b32 v[26:27], v46 offset0:214 offset1:247
	v_lshlrev_b32_e32 v0, 11, v0
	s_waitcnt lgkmcnt(0)
	v_cvt_pk_bf16_f32 v23, v26, v27
	v_lshl_add_u64 v[26:27], v[24:25], 0, v[0:1]
	global_store_dwordx4 v[26:27], v[20:23], off sc1
	ds_read2_b32 v[20:21], v46 offset0:24 offset1:57
	v_or_b32_e32 v0, s72, v49
	s_waitcnt lgkmcnt(0)
	v_cvt_pk_bf16_f32 v20, v20, v21
	ds_read2_b32 v[22:23], v46 offset0:90 offset1:123
	v_lshlrev_b32_e32 v0, 11, v0
	s_waitcnt lgkmcnt(0)
	v_cvt_pk_bf16_f32 v21, v22, v23
	ds_read2_b32 v[22:23], v46 offset0:156 offset1:189
	v_lshl_add_u64 v[24:25], v[24:25], 0, v[0:1]
	s_waitcnt lgkmcnt(0)
	v_cvt_pk_bf16_f32 v22, v22, v23
	ds_read2_b32 v[26:27], v46 offset0:222 offset1:255
	s_waitcnt lgkmcnt(0)
	v_cvt_pk_bf16_f32 v23, v26, v27
	global_store_dwordx4 v[24:25], v[20:23], off sc1
	s_waitcnt lgkmcnt(0)

; #define LAS __attribute__((address_space(3)))
; __device__ __forceinline__ unsigned cvt_pk_bf16(float lo, float hi) { unsigned r; asm volatile("v_cvt_pk_bf16_f32 %0, %1, %2" : "=v"(r) : "v"(lo), "v"(hi)); return r; }
; __device__ __forceinline__ void wconv_item(const float* W, int K, int Norig, int Nphys, bf16_t* WT, const float* gA, const float* gB, int split, int mapid, LAS float* scr, int item, int lane) {
;     ...
;     for (int i = 0; i < 32; ++i) { const int kk = 2 * i + (lane >> 5), k = k0 + kk;
;         float v = wv[i];
;         if (gA) v *= (k < split ? gA[k] : gB[k - split]);
;         scr[kk * 33 + (lane & 31)] = v; }
;     asm volatile("s_waitcnt lgkmcnt(0)" ::: "memory");
;     const int c = lane & 7;
; #pragma unroll
;     for (int j = 0; j < 4; ++j) { const int n = (lane >> 3) + 8 * j; const LAS float* s = scr + (8 * c) * 33 + n;
;         u32x4 o; o.x = cvt_pk_bf16(s[0 * 33], s[1 * 33]); o.y = cvt_pk_bf16(s[2 * 33], s[3 * 33]); o.z = cvt_pk_bf16(s[4 * 33], s[5 * 33]); o.w = cvt_pk_bf16(s[6 * 33], s[7 * 33]);
;         *(u32x4*)(WT + (size_t)(n0 + n) * K + k0 + 8 * c) = o; }
;     asm volatile("s_waitcnt lgkmcnt(0)" ::: "memory");
.LBB0_1120:
	v_add_u32_e32 v0, v43, v80
	v_add_u32_e32 v0, 0x400, v0
	ds_write2_b32 v0, v24, v25 offset0:8 offset1:74
	ds_write2_b32 v0, v26, v27 offset0:140 offset1:206
	s_waitcnt lgkmcnt(0)
	ds_read2_b32 v[20:21], v46 offset1:33
	s_waitcnt lgkmcnt(0)
	v_cvt_pk_bf16_f32 v20, v20, v21
	ds_read2_b32 v[22:23], v46 offset0:66 offset1:99
	s_waitcnt lgkmcnt(0)
	v_cvt_pk_bf16_f32 v21, v22, v23
	ds_read2_b32 v[22:23], v46 offset0:132 offset1:165
	v_or_b32_e32 v0, s72, v45
	v_lshl_add_u64 v[24:25], s[48:49], 1, v[12:13]
	s_waitcnt lgkmcnt(0)
	v_cvt_pk_bf16_f32 v22, v22, v23
	ds_read2_b32 v[26:27], v46 offset0:198 offset1:231
	v_lshlrev_b32_e32 v0, 11, v0
	s_waitcnt lgkmcnt(0)
	v_cvt_pk_bf16_f32 v23, v26, v27
	v_lshl_add_u64 v[26:27], v[24:25], 0, v[0:1]
	global_store_dwordx4 v[26:27], v[20:23], off sc1
	ds_read2_b32 v[20:21], v46 offset0:8 offset1:41
	v_or_b32_e32 v0, s72, v47
	s_waitcnt lgkmcnt(0)
	v_cvt_pk_bf16_f32 v20, v20, v21
	ds_read2_b32 v[22:23], v46 offset0:74 offset1:107
	s_waitcnt lgkmcnt(0)
	v_cvt_pk_bf16_f32 v21, v22, v23
	ds_read2_b32 v[22:23], v46 offset0:140 offset1:173
	s_waitcnt lgkmcnt(0)
	v_cvt_pk_bf16_f32 v22, v22, v23
	ds_read2_b32 v[26:27], v46 offset0:206 offset1:239
	v_lshlrev_b32_e32 v0, 11, v0
	s_waitcnt lgkmcnt(0)
	v_cvt_pk_bf16_f32 v23, v26, v27
	v_lshl_add_u64 v[26:27], v[24:25], 0, v[0:1]
	global_store_dwordx4 v[26:27], v[20:23], off sc1
	ds_read2_b32 v[20:21], v46 offset0:16 offset1:49
	v_or_b32_e32 v0, s72, v48
	s_waitcnt lgkmcnt(0)
	v_cvt_pk_bf16_f32 v20, v20, v21
	ds_read2_b32 v[22:23], v46 offset0:82 offset1:115
	s_waitcnt lgkmcnt(0)
	v_cvt_pk_bf16_f32 v21, v22, v23
	ds_read2_b32 v[22:23], v46 offset0:148 offset1:181
	s_waitcnt lgkmcnt(0)
	v_cvt_pk_bf16_f32 v22, v22, v23
	ds_read2_b32 v[26:27], v46 offset0:214 offset1:247
	v_lshlrev_b32_e32 v0, 11, v0
	s_waitcnt lgkmcnt(0)
	v_cvt_pk_bf16_f32 v23, v26, v27
	v_lshl_add_u64 v[26:27], v[24:25], 0, v[0:1]
	global_store_dwordx4 v[26:27], v[20:23], off sc1
	ds_read2_b32 v[20:21], v46 offset0:24 offset1:57
	v_or_b32_e32 v0, s72, v49
	s_waitcnt lgkmcnt(0)
	v_cvt_pk_bf16_f32 v20, v20, v21
	ds_read2_b32 v[22:23], v46 offset0:90 offset1:123
	v_lshlrev_b32_e32 v0, 11, v0
	s_waitcnt lgkmcnt(0)
	v_cvt_pk_bf16_f32 v21, v22, v23
	ds_read2_b32 v[22:23], v46 offset0:156 offset1:189
	v_lshl_add_u64 v[24:25], v[24:25], 0, v[0:1]
	s_waitcnt lgkmcnt(0)
	v_cvt_pk_bf16_f32 v22, v22, v23
	ds_read2_b32 v[26:27], v46 offset0:222 offset1:255
	s_waitcnt lgkmcnt(0)
	v_cvt_pk_bf16_f32 v23, v26, v27
	global_store_dwordx4 v[24:25], v[20:23], off sc1
	s_waitcnt lgkmcnt(0)

; #define LAS __attribute__((address_space(3)))
; __device__ __forceinline__ unsigned cvt_pk_bf16(float lo, float hi) { unsigned r; asm volatile("v_cvt_pk_bf16_f32 %0, %1, %2" : "=v"(r) : "v"(lo), "v"(hi)); return r; }
; __device__ __forceinline__ void wconv_item(const float* W, int K, int Norig, int Nphys, bf16_t* WT, const float* gA, const float* gB, int split, int mapid, LAS float* scr, int item, int lane) {
;     ...
;     for (int i = 0; i < 32; ++i) { const int kk = 2 * i + (lane >> 5), k = k0 + kk;
;         float v = wv[i];
;         if (gA) v *= (k < split ? gA[k] : gB[k - split]);
;         scr[kk * 33 + (lane & 31)] = v; }
;     asm volatile("s_waitcnt lgkmcnt(0)" ::: "memory");
;     const int c = lane & 7;
; #pragma unroll
;     for (int j = 0; j < 4; ++j) { const int n = (lane >> 3) + 8 * j; const LAS float* s = scr + (8 * c) * 33 + n;
;         u32x4 o; o.x = cvt_pk_bf16(s[0 * 33], s[1 * 33]); o.y = cvt_pk_bf16(s[2 * 33], s[3 * 33]); o.z = cvt_pk_bf16(s[4 * 33], s[5 * 33]); o.w = cvt_pk_bf16(s[6 * 33], s[7 * 33]);
;         *(u32x4*)(WT + (size_t)(n0 + n) * K + k0 + 8 * c) = o; }
;     asm volatile("s_waitcnt lgkmcnt(0)" ::: "memory");
.LBB0_1139:
	v_add_u32_e32 v0, v43, v80
	v_add_u32_e32 v0, 0x400, v0
	ds_write2_b32 v0, v24, v25 offset0:8 offset1:74
	ds_write2_b32 v0, v26, v27 offset0:140 offset1:206
	s_waitcnt lgkmcnt(0)
	ds_read2_b32 v[20:21], v46 offset1:33
	s_waitcnt lgkmcnt(0)
	v_cvt_pk_bf16_f32 v20, v20, v21
	ds_read2_b32 v[22:23], v46 offset0:66 offset1:99
	s_lshl_b32 s48, s48, 1
	s_waitcnt lgkmcnt(0)
	v_cvt_pk_bf16_f32 v21, v22, v23
	ds_read2_b32 v[22:23], v46 offset0:132 offset1:165
	v_or_b32_e32 v0, s72, v45
	v_lshl_add_u64 v[24:25], v[14:15], 0, s[48:49]
	s_waitcnt lgkmcnt(0)
	v_cvt_pk_bf16_f32 v22, v22, v23
	ds_read2_b32 v[26:27], v46 offset0:198 offset1:231
	v_lshlrev_b32_e32 v0, 9, v0
	s_waitcnt lgkmcnt(0)
	v_cvt_pk_bf16_f32 v23, v26, v27
	v_lshl_add_u64 v[26:27], v[24:25], 0, v[0:1]
	global_store_dwordx4 v[26:27], v[20:23], off sc1
	ds_read2_b32 v[20:21], v46 offset0:8 offset1:41
	v_or_b32_e32 v0, s72, v47
	s_waitcnt lgkmcnt(0)
	v_cvt_pk_bf16_f32 v20, v20, v21
	ds_read2_b32 v[22:23], v46 offset0:74 offset1:107
	s_waitcnt lgkmcnt(0)
	v_cvt_pk_bf16_f32 v21, v22, v23
	ds_read2_b32 v[22:23], v46 offset0:140 offset1:173
	s_waitcnt lgkmcnt(0)
	v_cvt_pk_bf16_f32 v22, v22, v23
	ds_read2_b32 v[26:27], v46 offset0:206 offset1:239
	v_lshlrev_b32_e32 v0, 9, v0
	s_waitcnt lgkmcnt(0)
	v_cvt_pk_bf16_f32 v23, v26, v27
	v_lshl_add_u64 v[26:27], v[24:25], 0, v[0:1]
	global_store_dwordx4 v[26:27], v[20:23], off sc1
	ds_read2_b32 v[20:21], v46 offset0:16 offset1:49
	v_or_b32_e32 v0, s72, v48
	s_waitcnt lgkmcnt(0)
	v_cvt_pk_bf16_f32 v20, v20, v21
	ds_read2_b32 v[22:23], v46 offset0:82 offset1:115
	s_waitcnt lgkmcnt(0)
	v_cvt_pk_bf16_f32 v21, v22, v23
	ds_read2_b32 v[22:23], v46 offset0:148 offset1:181
	s_waitcnt lgkmcnt(0)
	v_cvt_pk_bf16_f32 v22, v22, v23
	ds_read2_b32 v[26:27], v46 offset0:214 offset1:247
	v_lshlrev_b32_e32 v0, 9, v0
	s_waitcnt lgkmcnt(0)
	v_cvt_pk_bf16_f32 v23, v26, v27
	v_lshl_add_u64 v[26:27], v[24:25], 0, v[0:1]
	global_store_dwordx4 v[26:27], v[20:23], off sc1
	ds_read2_b32 v[20:21], v46 offset0:24 offset1:57
	v_or_b32_e32 v0, s72, v49
	s_waitcnt lgkmcnt(0)
	v_cvt_pk_bf16_f32 v20, v20, v21
	ds_read2_b32 v[22:23], v46 offset0:90 offset1:123
	v_lshlrev_b32_e32 v0, 9, v0
	s_waitcnt lgkmcnt(0)
	v_cvt_pk_bf16_f32 v21, v22, v23
	ds_read2_b32 v[22:23], v46 offset0:156 offset1:189
	v_lshl_add_u64 v[24:25], v[24:25], 0, v[0:1]
	s_waitcnt lgkmcnt(0)
	v_cvt_pk_bf16_f32 v22, v22, v23
	ds_read2_b32 v[26:27], v46 offset0:222 offset1:255
	s_waitcnt lgkmcnt(0)
	v_cvt_pk_bf16_f32 v23, v26, v27
	global_store_dwordx4 v[24:25], v[20:23], off sc1
	s_waitcnt lgkmcnt(0)

; #define LAS __attribute__((address_space(3)))
; __device__ __forceinline__ unsigned cvt_pk_bf16(float lo, float hi) { unsigned r; asm volatile("v_cvt_pk_bf16_f32 %0, %1, %2" : "=v"(r) : "v"(lo), "v"(hi)); return r; }
; __device__ __forceinline__ void wconv_item(const float* W, int K, int Norig, int Nphys, bf16_t* WT, const float* gA, const float* gB, int split, int mapid, LAS float* scr, int item, int lane) {
;     ...
;     for (int i = 0; i < 32; ++i) { const int kk = 2 * i + (lane >> 5), k = k0 + kk;
;         float v = wv[i];
;         if (gA) v *= (k < split ? gA[k] : gB[k - split]);
;         scr[kk * 33 + (lane & 31)] = v; }
;     asm volatile("s_waitcnt lgkmcnt(0)" ::: "memory");
;     const int c = lane & 7;
; #pragma unroll
;     for (int j = 0; j < 4; ++j) { const int n = (lane >> 3) + 8 * j; const LAS float* s = scr + (8 * c) * 33 + n;
;         u32x4 o; o.x = cvt_pk_bf16(s[0 * 33], s[1 * 33]); o.y = cvt_pk_bf16(s[2 * 33], s[3 * 33]); o.z = cvt_pk_bf16(s[4 * 33], s[5 * 33]); o.w = cvt_pk_bf16(s[6 * 33], s[7 * 33]);
;         *(u32x4*)(WT + (size_t)(n0 + n) * K + k0 + 8 * c) = o; }
;     asm volatile("s_waitcnt lgkmcnt(0)" ::: "memory");
.LBB0_1158:
	v_add_u32_e32 v0, v43, v80
	v_add_u32_e32 v0, 0x400, v0
	ds_write2_b32 v0, v24, v25 offset0:8 offset1:74
	ds_write2_b32 v0, v26, v27 offset0:140 offset1:206
	s_waitcnt lgkmcnt(0)
	s_lshl_b32 s38, s48, 5
	ds_read2_b32 v[22:23], v46 offset1:33
	s_waitcnt lgkmcnt(0)
	v_cvt_pk_bf16_f32 v22, v22, v23
	ds_read2_b32 v[24:25], v46 offset0:66 offset1:99
	v_or_b32_e32 v0, s38, v45
	s_lshl_b32 s48, s72, 1
	s_waitcnt lgkmcnt(0)
	v_cvt_pk_bf16_f32 v23, v24, v25
	ds_read2_b32 v[24:25], v46 offset0:132 offset1:165
	v_mul_u32_u24_e32 v0, 0x180, v0
	v_lshl_add_u64 v[20:21], v[16:17], 0, s[48:49]
	s_waitcnt lgkmcnt(0)
	v_cvt_pk_bf16_f32 v24, v24, v25
	ds_read2_b32 v[26:27], v46 offset0:198 offset1:231
	v_lshlrev_b32_e32 v0, 1, v0
	s_waitcnt lgkmcnt(0)
	v_cvt_pk_bf16_f32 v25, v26, v27
	v_lshl_add_u64 v[26:27], v[20:21], 0, v[0:1]
	global_store_dwordx4 v[26:27], v[22:25], off sc1
	ds_read2_b32 v[22:23], v46 offset0:8 offset1:41
	v_or_b32_e32 v0, s38, v47
	s_waitcnt lgkmcnt(0)
	v_cvt_pk_bf16_f32 v22, v22, v23
	ds_read2_b32 v[24:25], v46 offset0:74 offset1:107
	s_waitcnt lgkmcnt(0)
	v_cvt_pk_bf16_f32 v23, v24, v25
	ds_read2_b32 v[24:25], v46 offset0:140 offset1:173
	v_mul_u32_u24_e32 v0, 0x180, v0
	s_waitcnt lgkmcnt(0)
	v_cvt_pk_bf16_f32 v24, v24, v25
	ds_read2_b32 v[26:27], v46 offset0:206 offset1:239
	v_lshlrev_b32_e32 v0, 1, v0
	s_waitcnt lgkmcnt(0)
	v_cvt_pk_bf16_f32 v25, v26, v27
	v_lshl_add_u64 v[26:27], v[20:21], 0, v[0:1]
	global_store_dwordx4 v[26:27], v[22:25], off sc1
	ds_read2_b32 v[22:23], v46 offset0:16 offset1:49
	v_or_b32_e32 v0, s38, v48
	s_waitcnt lgkmcnt(0)
	v_cvt_pk_bf16_f32 v22, v22, v23
	ds_read2_b32 v[24:25], v46 offset0:82 offset1:115
	s_waitcnt lgkmcnt(0)
	v_cvt_pk_bf16_f32 v23, v24, v25
	ds_read2_b32 v[24:25], v46 offset0:148 offset1:181
	v_mul_u32_u24_e32 v0, 0x180, v0
	s_waitcnt lgkmcnt(0)
	v_cvt_pk_bf16_f32 v24, v24, v25
	ds_read2_b32 v[26:27], v46 offset0:214 offset1:247
	v_lshlrev_b32_e32 v0, 1, v0
	s_waitcnt lgkmcnt(0)
	v_cvt_pk_bf16_f32 v25, v26, v27
	v_lshl_add_u64 v[26:27], v[20:21], 0, v[0:1]
	v_or_b32_e32 v0, s38, v49
	global_store_dwordx4 v[26:27], v[22:25], off sc1
	ds_read2_b32 v[22:23], v46 offset0:24 offset1:57
	v_mul_u32_u24_e32 v0, 0x180, v0
	s_waitcnt lgkmcnt(0)
	v_cvt_pk_bf16_f32 v22, v22, v23
	ds_read2_b32 v[24:25], v46 offset0:90 offset1:123
	v_lshlrev_b32_e32 v0, 1, v0
	s_waitcnt lgkmcnt(0)
	v_cvt_pk_bf16_f32 v23, v24, v25
	ds_read2_b32 v[24:25], v46 offset0:156 offset1:189
	v_lshl_add_u64 v[20:21], v[20:21], 0, v[0:1]
	s_waitcnt lgkmcnt(0)
	v_cvt_pk_bf16_f32 v24, v24, v25
	ds_read2_b32 v[26:27], v46 offset0:222 offset1:255
	s_waitcnt lgkmcnt(0)
	v_cvt_pk_bf16_f32 v25, v26, v27
	global_store_dwordx4 v[20:21], v[22:25], off sc1
	s_waitcnt lgkmcnt(0)
